# batched the split-K partial fold loads in the four norm phases (was a serial load-wait-add chain)
# speedup vs baseline: 1.0437x; 1.0090x over previous
; template <bool FIRST, bool P8>
; __device__ __forceinline__ void phase_norm(Ctx& C, const float* nw, const float* w8src  , int ld8, int npart) {
;     ...
;         if (!FIRST && m >= MP && npart > 0) {
;             const bf16* pp = (const bf16*)(C.ws + WS_PART) + (size_t)(m - MP) * D + 4 * lane;
;             for (int ks = 0; ks < npart; ++ks) {
; #pragma unroll
;                 for (int j = 0; j < 4; ++j) { const v2u pw = *(const v2u*)(pp + (size_t)ks * MS * D + 256 * j); v[j] += (f32x4){bflo(pw.x), bfhi(pw.x), bflo(pw.y), bfhi(pw.y)}; } }
.LBB0_80:
	s_mov_b32 s4, 0xc800000
	s_mov_b32 s5, 0x0
	v_lshl_add_u64 v[72:73], v[32:33], 0, s[4:5]
	global_load_dwordx2 v[74:75], v[72:73], off
	global_load_dwordx2 v[76:77], v[72:73], off offset:512
	global_load_dwordx2 v[78:79], v[72:73], off offset:1024
	global_load_dwordx2 v[72:73], v[72:73], off offset:1536
	s_mov_b32 s4, 0xca00000
	s_mov_b32 s5, 0x0
	v_lshl_add_u64 v[80:81], v[32:33], 0, s[4:5]
	global_load_dwordx2 v[82:83], v[80:81], off
	global_load_dwordx2 v[84:85], v[80:81], off offset:512
	global_load_dwordx2 v[86:87], v[80:81], off offset:1024
	global_load_dwordx2 v[80:81], v[80:81], off offset:1536
	s_mov_b32 s4, 0xcc00000
	s_mov_b32 s5, 0x0
	v_lshl_add_u64 v[88:89], v[32:33], 0, s[4:5]
	global_load_dwordx2 v[90:91], v[88:89], off
	global_load_dwordx2 v[92:93], v[88:89], off offset:512
	global_load_dwordx2 v[94:95], v[88:89], off offset:1024
	global_load_dwordx2 v[88:89], v[88:89], off offset:1536
	s_mov_b32 s4, 0xce00000
	s_mov_b32 s5, 0x0
	v_lshl_add_u64 v[96:97], v[32:33], 0, s[4:5]
	global_load_dwordx2 v[98:99], v[96:97], off
	global_load_dwordx2 v[100:101], v[96:97], off offset:512
	global_load_dwordx2 v[102:103], v[96:97], off offset:1024
	global_load_dwordx2 v[96:97], v[96:97], off offset:1536
	s_mov_b32 s4, 0xd000000
	s_mov_b32 s5, 0x0
	v_lshl_add_u64 v[104:105], v[32:33], 0, s[4:5]
	global_load_dwordx2 v[106:107], v[104:105], off
	global_load_dwordx2 v[108:109], v[104:105], off offset:512
	global_load_dwordx2 v[110:111], v[104:105], off offset:1024
	global_load_dwordx2 v[104:105], v[104:105], off offset:1536
	s_mov_b32 s4, 0xd200000
	s_mov_b32 s5, 0x0
	v_lshl_add_u64 v[112:113], v[32:33], 0, s[4:5]
	global_load_dwordx2 v[114:115], v[112:113], off
	global_load_dwordx2 v[116:117], v[112:113], off offset:512
	global_load_dwordx2 v[118:119], v[112:113], off offset:1024
	global_load_dwordx2 v[112:113], v[112:113], off offset:1536
	s_mov_b32 s4, 0xd400000
	s_mov_b32 s5, 0x0
	v_lshl_add_u64 v[120:121], v[32:33], 0, s[4:5]
	global_load_dwordx2 v[122:123], v[120:121], off
	global_load_dwordx2 v[124:125], v[120:121], off offset:512
	global_load_dwordx2 v[126:127], v[120:121], off offset:1024
	global_load_dwordx2 v[120:121], v[120:121], off offset:1536
	s_mov_b32 s4, 0xd600000
	s_mov_b32 s5, 0x0
	v_lshl_add_u64 v[128:129], v[32:33], 0, s[4:5]
	global_load_dwordx2 v[130:131], v[128:129], off
	global_load_dwordx2 v[132:133], v[128:129], off offset:512
	global_load_dwordx2 v[134:135], v[128:129], off offset:1024
	global_load_dwordx2 v[128:129], v[128:129], off offset:1536
	s_waitcnt vmcnt(31)
	v_lshlrev_b32_e32 v68, 16, v74
	v_and_b32_e32 v69, 0xffff0000, v74
	v_lshlrev_b32_e32 v70, 16, v75
	v_and_b32_e32 v71, 0xffff0000, v75
	v_pk_add_f32 v[42:43], v[42:43], v[68:69]
	v_pk_add_f32 v[40:41], v[40:41], v[70:71]
	s_waitcnt vmcnt(30)
	v_lshlrev_b32_e32 v68, 16, v76
	v_and_b32_e32 v69, 0xffff0000, v76
	v_lshlrev_b32_e32 v70, 16, v77
	v_and_b32_e32 v71, 0xffff0000, v77
	v_pk_add_f32 v[38:39], v[38:39], v[68:69]
	v_pk_add_f32 v[36:37], v[36:37], v[70:71]
	s_waitcnt vmcnt(29)
	v_lshlrev_b32_e32 v68, 16, v78
	v_and_b32_e32 v69, 0xffff0000, v78
	v_lshlrev_b32_e32 v70, 16, v79
	v_and_b32_e32 v71, 0xffff0000, v79
	v_pk_add_f32 v[34:35], v[34:35], v[68:69]
	v_pk_add_f32 v[30:31], v[30:31], v[70:71]
	s_waitcnt vmcnt(28)
	v_lshlrev_b32_e32 v68, 16, v72
	v_and_b32_e32 v69, 0xffff0000, v72
	v_lshlrev_b32_e32 v70, 16, v73
	v_and_b32_e32 v71, 0xffff0000, v73
	v_pk_add_f32 v[28:29], v[28:29], v[68:69]
	v_pk_add_f32 v[26:27], v[26:27], v[70:71]
	s_waitcnt vmcnt(27)
	v_lshlrev_b32_e32 v68, 16, v82
	v_and_b32_e32 v69, 0xffff0000, v82
	v_lshlrev_b32_e32 v70, 16, v83
	v_and_b32_e32 v71, 0xffff0000, v83
	v_pk_add_f32 v[42:43], v[42:43], v[68:69]
	v_pk_add_f32 v[40:41], v[40:41], v[70:71]
	s_waitcnt vmcnt(26)
	v_lshlrev_b32_e32 v68, 16, v84
	v_and_b32_e32 v69, 0xffff0000, v84
	v_lshlrev_b32_e32 v70, 16, v85
	v_and_b32_e32 v71, 0xffff0000, v85
	v_pk_add_f32 v[38:39], v[38:39], v[68:69]
	v_pk_add_f32 v[36:37], v[36:37], v[70:71]
	s_waitcnt vmcnt(25)
	v_lshlrev_b32_e32 v68, 16, v86
	v_and_b32_e32 v69, 0xffff0000, v86
	v_lshlrev_b32_e32 v70, 16, v87
	v_and_b32_e32 v71, 0xffff0000, v87
	v_pk_add_f32 v[34:35], v[34:35], v[68:69]
	v_pk_add_f32 v[30:31], v[30:31], v[70:71]
	s_waitcnt vmcnt(24)
	v_lshlrev_b32_e32 v68, 16, v80
	v_and_b32_e32 v69, 0xffff0000, v80
	v_lshlrev_b32_e32 v70, 16, v81
	v_and_b32_e32 v71, 0xffff0000, v81
	v_pk_add_f32 v[28:29], v[28:29], v[68:69]
	v_pk_add_f32 v[26:27], v[26:27], v[70:71]
	s_waitcnt vmcnt(23)
	v_lshlrev_b32_e32 v68, 16, v90
	v_and_b32_e32 v69, 0xffff0000, v90
	v_lshlrev_b32_e32 v70, 16, v91
	v_and_b32_e32 v71, 0xffff0000, v91
	v_pk_add_f32 v[42:43], v[42:43], v[68:69]
	v_pk_add_f32 v[40:41], v[40:41], v[70:71]
	s_waitcnt vmcnt(22)
	v_lshlrev_b32_e32 v68, 16, v92
	v_and_b32_e32 v69, 0xffff0000, v92
	v_lshlrev_b32_e32 v70, 16, v93
	v_and_b32_e32 v71, 0xffff0000, v93
	v_pk_add_f32 v[38:39], v[38:39], v[68:69]
	v_pk_add_f32 v[36:37], v[36:37], v[70:71]
	s_waitcnt vmcnt(21)
	v_lshlrev_b32_e32 v68, 16, v94
	v_and_b32_e32 v69, 0xffff0000, v94
	v_lshlrev_b32_e32 v70, 16, v95
	v_and_b32_e32 v71, 0xffff0000, v95
	v_pk_add_f32 v[34:35], v[34:35], v[68:69]
	v_pk_add_f32 v[30:31], v[30:31], v[70:71]
	s_waitcnt vmcnt(20)
	v_lshlrev_b32_e32 v68, 16, v88
	v_and_b32_e32 v69, 0xffff0000, v88
	v_lshlrev_b32_e32 v70, 16, v89
	v_and_b32_e32 v71, 0xffff0000, v89
	v_pk_add_f32 v[28:29], v[28:29], v[68:69]
	v_pk_add_f32 v[26:27], v[26:27], v[70:71]
	s_waitcnt vmcnt(19)
	v_lshlrev_b32_e32 v68, 16, v98
	v_and_b32_e32 v69, 0xffff0000, v98
	v_lshlrev_b32_e32 v70, 16, v99
	v_and_b32_e32 v71, 0xffff0000, v99
	v_pk_add_f32 v[42:43], v[42:43], v[68:69]
	v_pk_add_f32 v[40:41], v[40:41], v[70:71]
	s_waitcnt vmcnt(18)
; template <bool FIRST, bool P8>
; __device__ __forceinline__ void phase_norm(Ctx& C, const float* nw, const float* w8src  , int ld8, int npart) {
;     ...
;         if (!FIRST && m >= MP && npart > 0) {
;             const bf16* pp = (const bf16*)(C.ws + WS_PART) + (size_t)(m - MP) * D + 4 * lane;
;             for (int ks = 0; ks < npart; ++ks) {
; #pragma unroll
;                 for (int j = 0; j < 4; ++j) { const v2u pw = *(const v2u*)(pp + (size_t)ks * MS * D + 256 * j); v[j] += (f32x4){bflo(pw.x), bfhi(pw.x), bflo(pw.y), bfhi(pw.y)}; } }
	v_lshlrev_b32_e32 v68, 16, v100
	v_and_b32_e32 v69, 0xffff0000, v100
	v_lshlrev_b32_e32 v70, 16, v101
	v_and_b32_e32 v71, 0xffff0000, v101
	v_pk_add_f32 v[38:39], v[38:39], v[68:69]
	v_pk_add_f32 v[36:37], v[36:37], v[70:71]
	s_waitcnt vmcnt(17)
	v_lshlrev_b32_e32 v68, 16, v102
	v_and_b32_e32 v69, 0xffff0000, v102
	v_lshlrev_b32_e32 v70, 16, v103
	v_and_b32_e32 v71, 0xffff0000, v103
	v_pk_add_f32 v[34:35], v[34:35], v[68:69]
	v_pk_add_f32 v[30:31], v[30:31], v[70:71]
	s_waitcnt vmcnt(16)
	v_lshlrev_b32_e32 v68, 16, v96
	v_and_b32_e32 v69, 0xffff0000, v96
	v_lshlrev_b32_e32 v70, 16, v97
	v_and_b32_e32 v71, 0xffff0000, v97
	v_pk_add_f32 v[28:29], v[28:29], v[68:69]
	v_pk_add_f32 v[26:27], v[26:27], v[70:71]
	s_waitcnt vmcnt(15)
	v_lshlrev_b32_e32 v68, 16, v106
	v_and_b32_e32 v69, 0xffff0000, v106
	v_lshlrev_b32_e32 v70, 16, v107
	v_and_b32_e32 v71, 0xffff0000, v107
	v_pk_add_f32 v[42:43], v[42:43], v[68:69]
	v_pk_add_f32 v[40:41], v[40:41], v[70:71]
	s_waitcnt vmcnt(14)
	v_lshlrev_b32_e32 v68, 16, v108
	v_and_b32_e32 v69, 0xffff0000, v108
	v_lshlrev_b32_e32 v70, 16, v109
	v_and_b32_e32 v71, 0xffff0000, v109
	v_pk_add_f32 v[38:39], v[38:39], v[68:69]
	v_pk_add_f32 v[36:37], v[36:37], v[70:71]
	s_waitcnt vmcnt(13)
	v_lshlrev_b32_e32 v68, 16, v110
	v_and_b32_e32 v69, 0xffff0000, v110
	v_lshlrev_b32_e32 v70, 16, v111
	v_and_b32_e32 v71, 0xffff0000, v111
	v_pk_add_f32 v[34:35], v[34:35], v[68:69]
	v_pk_add_f32 v[30:31], v[30:31], v[70:71]
	s_waitcnt vmcnt(12)
	v_lshlrev_b32_e32 v68, 16, v104
	v_and_b32_e32 v69, 0xffff0000, v104
	v_lshlrev_b32_e32 v70, 16, v105
	v_and_b32_e32 v71, 0xffff0000, v105
	v_pk_add_f32 v[28:29], v[28:29], v[68:69]
	v_pk_add_f32 v[26:27], v[26:27], v[70:71]
	s_waitcnt vmcnt(11)
	v_lshlrev_b32_e32 v68, 16, v114
	v_and_b32_e32 v69, 0xffff0000, v114
	v_lshlrev_b32_e32 v70, 16, v115
	v_and_b32_e32 v71, 0xffff0000, v115
	v_pk_add_f32 v[42:43], v[42:43], v[68:69]
	v_pk_add_f32 v[40:41], v[40:41], v[70:71]
	s_waitcnt vmcnt(10)
	v_lshlrev_b32_e32 v68, 16, v116
	v_and_b32_e32 v69, 0xffff0000, v116
	v_lshlrev_b32_e32 v70, 16, v117
	v_and_b32_e32 v71, 0xffff0000, v117
	v_pk_add_f32 v[38:39], v[38:39], v[68:69]
	v_pk_add_f32 v[36:37], v[36:37], v[70:71]
	s_waitcnt vmcnt(9)
	v_lshlrev_b32_e32 v68, 16, v118
	v_and_b32_e32 v69, 0xffff0000, v118
	v_lshlrev_b32_e32 v70, 16, v119
	v_and_b32_e32 v71, 0xffff0000, v119
	v_pk_add_f32 v[34:35], v[34:35], v[68:69]
	v_pk_add_f32 v[30:31], v[30:31], v[70:71]
	s_waitcnt vmcnt(8)
	v_lshlrev_b32_e32 v68, 16, v112
	v_and_b32_e32 v69, 0xffff0000, v112
	v_lshlrev_b32_e32 v70, 16, v113
	v_and_b32_e32 v71, 0xffff0000, v113
	v_pk_add_f32 v[28:29], v[28:29], v[68:69]
	v_pk_add_f32 v[26:27], v[26:27], v[70:71]
	s_waitcnt vmcnt(7)
	v_lshlrev_b32_e32 v68, 16, v122
	v_and_b32_e32 v69, 0xffff0000, v122
	v_lshlrev_b32_e32 v70, 16, v123
	v_and_b32_e32 v71, 0xffff0000, v123
	v_pk_add_f32 v[42:43], v[42:43], v[68:69]
	v_pk_add_f32 v[40:41], v[40:41], v[70:71]
	s_waitcnt vmcnt(6)
	v_lshlrev_b32_e32 v68, 16, v124
	v_and_b32_e32 v69, 0xffff0000, v124
	v_lshlrev_b32_e32 v70, 16, v125
	v_and_b32_e32 v71, 0xffff0000, v125
	v_pk_add_f32 v[38:39], v[38:39], v[68:69]
	v_pk_add_f32 v[36:37], v[36:37], v[70:71]
	s_waitcnt vmcnt(5)
	v_lshlrev_b32_e32 v68, 16, v126
	v_and_b32_e32 v69, 0xffff0000, v126
	v_lshlrev_b32_e32 v70, 16, v127
	v_and_b32_e32 v71, 0xffff0000, v127
	v_pk_add_f32 v[34:35], v[34:35], v[68:69]
	v_pk_add_f32 v[30:31], v[30:31], v[70:71]
	s_waitcnt vmcnt(4)
	v_lshlrev_b32_e32 v68, 16, v120
	v_and_b32_e32 v69, 0xffff0000, v120
	v_lshlrev_b32_e32 v70, 16, v121
	v_and_b32_e32 v71, 0xffff0000, v121
	v_pk_add_f32 v[28:29], v[28:29], v[68:69]
	v_pk_add_f32 v[26:27], v[26:27], v[70:71]
	s_waitcnt vmcnt(3)
	v_lshlrev_b32_e32 v68, 16, v130
	v_and_b32_e32 v69, 0xffff0000, v130
	v_lshlrev_b32_e32 v70, 16, v131
	v_and_b32_e32 v71, 0xffff0000, v131
	v_pk_add_f32 v[42:43], v[42:43], v[68:69]
	v_pk_add_f32 v[40:41], v[40:41], v[70:71]
	s_waitcnt vmcnt(2)
	v_lshlrev_b32_e32 v68, 16, v132
	v_and_b32_e32 v69, 0xffff0000, v132
	v_lshlrev_b32_e32 v70, 16, v133
	v_and_b32_e32 v71, 0xffff0000, v133
	v_pk_add_f32 v[38:39], v[38:39], v[68:69]
	v_pk_add_f32 v[36:37], v[36:37], v[70:71]
	s_waitcnt vmcnt(1)
	v_lshlrev_b32_e32 v68, 16, v134
	v_and_b32_e32 v69, 0xffff0000, v134
	v_lshlrev_b32_e32 v70, 16, v135
	v_and_b32_e32 v71, 0xffff0000, v135
	v_pk_add_f32 v[34:35], v[34:35], v[68:69]
	v_pk_add_f32 v[30:31], v[30:31], v[70:71]
	s_waitcnt vmcnt(0)
; template <bool FIRST, bool P8>
; __device__ __forceinline__ void phase_norm(Ctx& C, const float* nw, const float* w8src  , int ld8, int npart) {
;     ...
;         if (!FIRST && m >= MP && npart > 0) {
;             const bf16* pp = (const bf16*)(C.ws + WS_PART) + (size_t)(m - MP) * D + 4 * lane;
;             for (int ks = 0; ks < npart; ++ks) {
; #pragma unroll
;                 for (int j = 0; j < 4; ++j) { const v2u pw = *(const v2u*)(pp + (size_t)ks * MS * D + 256 * j); v[j] += (f32x4){bflo(pw.x), bfhi(pw.x), bflo(pw.y), bfhi(pw.y)}; } }
	v_lshlrev_b32_e32 v68, 16, v128
	v_and_b32_e32 v69, 0xffff0000, v128
	v_lshlrev_b32_e32 v70, 16, v129
	v_and_b32_e32 v71, 0xffff0000, v129
	v_pk_add_f32 v[28:29], v[28:29], v[68:69]
	v_pk_add_f32 v[26:27], v[26:27], v[70:71]
	s_mov_b32 s4, 0xd800000
	s_mov_b32 s5, 0x0
	v_lshl_add_u64 v[72:73], v[32:33], 0, s[4:5]
	global_load_dwordx2 v[74:75], v[72:73], off
	global_load_dwordx2 v[76:77], v[72:73], off offset:512
	global_load_dwordx2 v[78:79], v[72:73], off offset:1024
	global_load_dwordx2 v[72:73], v[72:73], off offset:1536
	s_mov_b32 s4, 0xda00000
	s_mov_b32 s5, 0x0
	v_lshl_add_u64 v[80:81], v[32:33], 0, s[4:5]
	global_load_dwordx2 v[82:83], v[80:81], off
	global_load_dwordx2 v[84:85], v[80:81], off offset:512
	global_load_dwordx2 v[86:87], v[80:81], off offset:1024
	global_load_dwordx2 v[80:81], v[80:81], off offset:1536
	s_mov_b32 s4, 0xdc00000
	s_mov_b32 s5, 0x0
	v_lshl_add_u64 v[88:89], v[32:33], 0, s[4:5]
	global_load_dwordx2 v[90:91], v[88:89], off
	global_load_dwordx2 v[92:93], v[88:89], off offset:512
	global_load_dwordx2 v[94:95], v[88:89], off offset:1024
	global_load_dwordx2 v[88:89], v[88:89], off offset:1536
	s_mov_b32 s4, 0xde00000
	s_mov_b32 s5, 0x0
	v_lshl_add_u64 v[96:97], v[32:33], 0, s[4:5]
	global_load_dwordx2 v[98:99], v[96:97], off
	global_load_dwordx2 v[100:101], v[96:97], off offset:512
	global_load_dwordx2 v[102:103], v[96:97], off offset:1024
	global_load_dwordx2 v[96:97], v[96:97], off offset:1536
	s_mov_b32 s4, 0xe000000
	s_mov_b32 s5, 0x0
	v_lshl_add_u64 v[104:105], v[32:33], 0, s[4:5]
	global_load_dwordx2 v[106:107], v[104:105], off
	global_load_dwordx2 v[108:109], v[104:105], off offset:512
	global_load_dwordx2 v[110:111], v[104:105], off offset:1024
	global_load_dwordx2 v[104:105], v[104:105], off offset:1536
	s_mov_b32 s4, 0xe200000
	s_mov_b32 s5, 0x0
	v_lshl_add_u64 v[112:113], v[32:33], 0, s[4:5]
	global_load_dwordx2 v[114:115], v[112:113], off
	global_load_dwordx2 v[116:117], v[112:113], off offset:512
	global_load_dwordx2 v[118:119], v[112:113], off offset:1024
	global_load_dwordx2 v[112:113], v[112:113], off offset:1536
	s_mov_b32 s4, 0xe400000
	s_mov_b32 s5, 0x0
	v_lshl_add_u64 v[120:121], v[32:33], 0, s[4:5]
	global_load_dwordx2 v[122:123], v[120:121], off
	global_load_dwordx2 v[124:125], v[120:121], off offset:512
	global_load_dwordx2 v[126:127], v[120:121], off offset:1024
	global_load_dwordx2 v[120:121], v[120:121], off offset:1536
	s_mov_b32 s4, 0xe600000
	s_mov_b32 s5, 0x0
	v_lshl_add_u64 v[128:129], v[32:33], 0, s[4:5]
	global_load_dwordx2 v[130:131], v[128:129], off
	global_load_dwordx2 v[132:133], v[128:129], off offset:512
	global_load_dwordx2 v[134:135], v[128:129], off offset:1024
	global_load_dwordx2 v[128:129], v[128:129], off offset:1536
	s_waitcnt vmcnt(31)
	v_lshlrev_b32_e32 v68, 16, v74
	v_and_b32_e32 v69, 0xffff0000, v74
	v_lshlrev_b32_e32 v70, 16, v75
	v_and_b32_e32 v71, 0xffff0000, v75
	v_pk_add_f32 v[42:43], v[42:43], v[68:69]
	v_pk_add_f32 v[40:41], v[40:41], v[70:71]
	s_waitcnt vmcnt(30)
	v_lshlrev_b32_e32 v68, 16, v76
	v_and_b32_e32 v69, 0xffff0000, v76
	v_lshlrev_b32_e32 v70, 16, v77
	v_and_b32_e32 v71, 0xffff0000, v77
	v_pk_add_f32 v[38:39], v[38:39], v[68:69]
	v_pk_add_f32 v[36:37], v[36:37], v[70:71]
	s_waitcnt vmcnt(29)
	v_lshlrev_b32_e32 v68, 16, v78
	v_and_b32_e32 v69, 0xffff0000, v78
	v_lshlrev_b32_e32 v70, 16, v79
	v_and_b32_e32 v71, 0xffff0000, v79
	v_pk_add_f32 v[34:35], v[34:35], v[68:69]
	v_pk_add_f32 v[30:31], v[30:31], v[70:71]
	s_waitcnt vmcnt(28)
	v_lshlrev_b32_e32 v68, 16, v72
	v_and_b32_e32 v69, 0xffff0000, v72
	v_lshlrev_b32_e32 v70, 16, v73
	v_and_b32_e32 v71, 0xffff0000, v73
	v_pk_add_f32 v[28:29], v[28:29], v[68:69]
	v_pk_add_f32 v[26:27], v[26:27], v[70:71]
	s_waitcnt vmcnt(27)
	v_lshlrev_b32_e32 v68, 16, v82
	v_and_b32_e32 v69, 0xffff0000, v82
	v_lshlrev_b32_e32 v70, 16, v83
	v_and_b32_e32 v71, 0xffff0000, v83
	v_pk_add_f32 v[42:43], v[42:43], v[68:69]
	v_pk_add_f32 v[40:41], v[40:41], v[70:71]
	s_waitcnt vmcnt(26)
	v_lshlrev_b32_e32 v68, 16, v84
	v_and_b32_e32 v69, 0xffff0000, v84
	v_lshlrev_b32_e32 v70, 16, v85
	v_and_b32_e32 v71, 0xffff0000, v85
	v_pk_add_f32 v[38:39], v[38:39], v[68:69]
	v_pk_add_f32 v[36:37], v[36:37], v[70:71]
	s_waitcnt vmcnt(25)
	v_lshlrev_b32_e32 v68, 16, v86
	v_and_b32_e32 v69, 0xffff0000, v86
	v_lshlrev_b32_e32 v70, 16, v87
	v_and_b32_e32 v71, 0xffff0000, v87
	v_pk_add_f32 v[34:35], v[34:35], v[68:69]
	v_pk_add_f32 v[30:31], v[30:31], v[70:71]
	s_waitcnt vmcnt(24)
	v_lshlrev_b32_e32 v68, 16, v80
	v_and_b32_e32 v69, 0xffff0000, v80
	v_lshlrev_b32_e32 v70, 16, v81
	v_and_b32_e32 v71, 0xffff0000, v81
	v_pk_add_f32 v[28:29], v[28:29], v[68:69]
	v_pk_add_f32 v[26:27], v[26:27], v[70:71]
	s_waitcnt vmcnt(23)
	v_lshlrev_b32_e32 v68, 16, v90
	v_and_b32_e32 v69, 0xffff0000, v90
	v_lshlrev_b32_e32 v70, 16, v91
	v_and_b32_e32 v71, 0xffff0000, v91
	v_pk_add_f32 v[42:43], v[42:43], v[68:69]
	v_pk_add_f32 v[40:41], v[40:41], v[70:71]
	s_waitcnt vmcnt(22)
	v_lshlrev_b32_e32 v68, 16, v92
	v_and_b32_e32 v69, 0xffff0000, v92
	v_lshlrev_b32_e32 v70, 16, v93
	v_and_b32_e32 v71, 0xffff0000, v93
	v_pk_add_f32 v[38:39], v[38:39], v[68:69]
	v_pk_add_f32 v[36:37], v[36:37], v[70:71]
	s_waitcnt vmcnt(21)
	v_lshlrev_b32_e32 v68, 16, v94
	v_and_b32_e32 v69, 0xffff0000, v94
	v_lshlrev_b32_e32 v70, 16, v95
	v_and_b32_e32 v71, 0xffff0000, v95
	v_pk_add_f32 v[34:35], v[34:35], v[68:69]
	v_pk_add_f32 v[30:31], v[30:31], v[70:71]
	s_waitcnt vmcnt(20)
	v_lshlrev_b32_e32 v68, 16, v88
	v_and_b32_e32 v69, 0xffff0000, v88
	v_lshlrev_b32_e32 v70, 16, v89
	v_and_b32_e32 v71, 0xffff0000, v89
	v_pk_add_f32 v[28:29], v[28:29], v[68:69]
	v_pk_add_f32 v[26:27], v[26:27], v[70:71]
	s_waitcnt vmcnt(19)
; __device__ __forceinline__ unsigned pk2(float lo, float hi) { return f2bf(lo) | (f2bf(hi) << 16); }
; template <bool FIRST, bool P8>
; __device__ __forceinline__ void phase_norm(Ctx& C, const float* nw, const float* w8src  , int ld8, int npart) {
;     ...
;         if (!FIRST && m >= MP && npart > 0) {
;             const bf16* pp = (const bf16*)(C.ws + WS_PART) + (size_t)(m - MP) * D + 4 * lane;
;             for (int ks = 0; ks < npart; ++ks) {
; #pragma unroll
;                 for (int j = 0; j < 4; ++j) { const v2u pw = *(const v2u*)(pp + (size_t)ks * MS * D + 256 * j); v[j] += (f32x4){bflo(pw.x), bfhi(pw.x), bflo(pw.y), bfhi(pw.y)}; } }
; #pragma unroll
;             for (int j = 0; j < 4; ++j) { v2u hw; hw.x = pk2(v[j].x, v[j].y); hw.y = pk2(v[j].z, v[j].w); *(v2u*)(hrow + 256 * j) = hw; }
;         }
	v_lshlrev_b32_e32 v68, 16, v98
	v_and_b32_e32 v69, 0xffff0000, v98
	v_lshlrev_b32_e32 v70, 16, v99
	v_and_b32_e32 v71, 0xffff0000, v99
	v_pk_add_f32 v[42:43], v[42:43], v[68:69]
	v_pk_add_f32 v[40:41], v[40:41], v[70:71]
	s_waitcnt vmcnt(18)
	v_lshlrev_b32_e32 v68, 16, v100
	v_and_b32_e32 v69, 0xffff0000, v100
	v_lshlrev_b32_e32 v70, 16, v101
	v_and_b32_e32 v71, 0xffff0000, v101
	v_pk_add_f32 v[38:39], v[38:39], v[68:69]
	v_pk_add_f32 v[36:37], v[36:37], v[70:71]
	s_waitcnt vmcnt(17)
	v_lshlrev_b32_e32 v68, 16, v102
	v_and_b32_e32 v69, 0xffff0000, v102
	v_lshlrev_b32_e32 v70, 16, v103
	v_and_b32_e32 v71, 0xffff0000, v103
	v_pk_add_f32 v[34:35], v[34:35], v[68:69]
	v_pk_add_f32 v[30:31], v[30:31], v[70:71]
	s_waitcnt vmcnt(16)
	v_lshlrev_b32_e32 v68, 16, v96
	v_and_b32_e32 v69, 0xffff0000, v96
	v_lshlrev_b32_e32 v70, 16, v97
	v_and_b32_e32 v71, 0xffff0000, v97
	v_pk_add_f32 v[28:29], v[28:29], v[68:69]
	v_pk_add_f32 v[26:27], v[26:27], v[70:71]
	s_waitcnt vmcnt(15)
	v_lshlrev_b32_e32 v68, 16, v106
	v_and_b32_e32 v69, 0xffff0000, v106
	v_lshlrev_b32_e32 v70, 16, v107
	v_and_b32_e32 v71, 0xffff0000, v107
	v_pk_add_f32 v[42:43], v[42:43], v[68:69]
	v_pk_add_f32 v[40:41], v[40:41], v[70:71]
	s_waitcnt vmcnt(14)
	v_lshlrev_b32_e32 v68, 16, v108
	v_and_b32_e32 v69, 0xffff0000, v108
	v_lshlrev_b32_e32 v70, 16, v109
	v_and_b32_e32 v71, 0xffff0000, v109
	v_pk_add_f32 v[38:39], v[38:39], v[68:69]
	v_pk_add_f32 v[36:37], v[36:37], v[70:71]
	s_waitcnt vmcnt(13)
	v_lshlrev_b32_e32 v68, 16, v110
	v_and_b32_e32 v69, 0xffff0000, v110
	v_lshlrev_b32_e32 v70, 16, v111
	v_and_b32_e32 v71, 0xffff0000, v111
	v_pk_add_f32 v[34:35], v[34:35], v[68:69]
	v_pk_add_f32 v[30:31], v[30:31], v[70:71]
	s_waitcnt vmcnt(12)
	v_lshlrev_b32_e32 v68, 16, v104
	v_and_b32_e32 v69, 0xffff0000, v104
	v_lshlrev_b32_e32 v70, 16, v105
	v_and_b32_e32 v71, 0xffff0000, v105
	v_pk_add_f32 v[28:29], v[28:29], v[68:69]
	v_pk_add_f32 v[26:27], v[26:27], v[70:71]
	s_waitcnt vmcnt(11)
	v_lshlrev_b32_e32 v68, 16, v114
	v_and_b32_e32 v69, 0xffff0000, v114
	v_lshlrev_b32_e32 v70, 16, v115
	v_and_b32_e32 v71, 0xffff0000, v115
	v_pk_add_f32 v[42:43], v[42:43], v[68:69]
	v_pk_add_f32 v[40:41], v[40:41], v[70:71]
	s_waitcnt vmcnt(10)
	v_lshlrev_b32_e32 v68, 16, v116
	v_and_b32_e32 v69, 0xffff0000, v116
	v_lshlrev_b32_e32 v70, 16, v117
	v_and_b32_e32 v71, 0xffff0000, v117
	v_pk_add_f32 v[38:39], v[38:39], v[68:69]
	v_pk_add_f32 v[36:37], v[36:37], v[70:71]
	s_waitcnt vmcnt(9)
	v_lshlrev_b32_e32 v68, 16, v118
	v_and_b32_e32 v69, 0xffff0000, v118
	v_lshlrev_b32_e32 v70, 16, v119
	v_and_b32_e32 v71, 0xffff0000, v119
	v_pk_add_f32 v[34:35], v[34:35], v[68:69]
	v_pk_add_f32 v[30:31], v[30:31], v[70:71]
	s_waitcnt vmcnt(8)
	v_lshlrev_b32_e32 v68, 16, v112
	v_and_b32_e32 v69, 0xffff0000, v112
	v_lshlrev_b32_e32 v70, 16, v113
	v_and_b32_e32 v71, 0xffff0000, v113
	v_pk_add_f32 v[28:29], v[28:29], v[68:69]
	v_pk_add_f32 v[26:27], v[26:27], v[70:71]
	s_waitcnt vmcnt(7)
	v_lshlrev_b32_e32 v68, 16, v122
	v_and_b32_e32 v69, 0xffff0000, v122
	v_lshlrev_b32_e32 v70, 16, v123
	v_and_b32_e32 v71, 0xffff0000, v123
	v_pk_add_f32 v[42:43], v[42:43], v[68:69]
	v_pk_add_f32 v[40:41], v[40:41], v[70:71]
	s_waitcnt vmcnt(6)
	v_lshlrev_b32_e32 v68, 16, v124
	v_and_b32_e32 v69, 0xffff0000, v124
	v_lshlrev_b32_e32 v70, 16, v125
	v_and_b32_e32 v71, 0xffff0000, v125
	v_pk_add_f32 v[38:39], v[38:39], v[68:69]
	v_pk_add_f32 v[36:37], v[36:37], v[70:71]
	s_waitcnt vmcnt(5)
	v_lshlrev_b32_e32 v68, 16, v126
	v_and_b32_e32 v69, 0xffff0000, v126
	v_lshlrev_b32_e32 v70, 16, v127
	v_and_b32_e32 v71, 0xffff0000, v127
	v_pk_add_f32 v[34:35], v[34:35], v[68:69]
	v_pk_add_f32 v[30:31], v[30:31], v[70:71]
	s_waitcnt vmcnt(4)
	v_lshlrev_b32_e32 v68, 16, v120
	v_and_b32_e32 v69, 0xffff0000, v120
	v_lshlrev_b32_e32 v70, 16, v121
	v_and_b32_e32 v71, 0xffff0000, v121
	v_pk_add_f32 v[28:29], v[28:29], v[68:69]
	v_pk_add_f32 v[26:27], v[26:27], v[70:71]
	s_waitcnt vmcnt(3)
	v_lshlrev_b32_e32 v68, 16, v130
	v_and_b32_e32 v69, 0xffff0000, v130
	v_lshlrev_b32_e32 v70, 16, v131
	v_and_b32_e32 v71, 0xffff0000, v131
	v_pk_add_f32 v[42:43], v[42:43], v[68:69]
	v_pk_add_f32 v[40:41], v[40:41], v[70:71]
	s_waitcnt vmcnt(2)
	v_lshlrev_b32_e32 v68, 16, v132
	v_and_b32_e32 v69, 0xffff0000, v132
	v_lshlrev_b32_e32 v70, 16, v133
	v_and_b32_e32 v71, 0xffff0000, v133
	v_pk_add_f32 v[38:39], v[38:39], v[68:69]
	v_pk_add_f32 v[36:37], v[36:37], v[70:71]
	s_waitcnt vmcnt(1)
	v_lshlrev_b32_e32 v68, 16, v134
	v_and_b32_e32 v69, 0xffff0000, v134
	v_lshlrev_b32_e32 v70, 16, v135
	v_and_b32_e32 v71, 0xffff0000, v135
	v_pk_add_f32 v[34:35], v[34:35], v[68:69]
	v_pk_add_f32 v[30:31], v[30:31], v[70:71]
	s_waitcnt vmcnt(0)
	v_lshlrev_b32_e32 v68, 16, v128
	v_and_b32_e32 v69, 0xffff0000, v128
	v_lshlrev_b32_e32 v70, 16, v129
	v_and_b32_e32 v71, 0xffff0000, v129
	v_pk_add_f32 v[28:29], v[28:29], v[68:69]
	v_pk_add_f32 v[26:27], v[26:27], v[70:71]
	s_mov_b32 s2, 0xca00000
	v_bfe_u32 v2, v42, 16, 1
	v_add3_u32 v2, v42, v2, s13
	v_bfe_u32 v32, v43, 16, 1
	v_lshrrev_b32_e32 v2, 16, v2
	v_add3_u32 v32, v43, v32, s13
	v_and_or_b32 v32, v32, s3, v2
	v_bfe_u32 v2, v40, 16, 1
	v_add3_u32 v2, v40, v2, s13
	v_bfe_u32 v33, v41, 16, 1
	v_lshrrev_b32_e32 v2, 16, v2
	v_add3_u32 v33, v41, v33, s13
	v_and_or_b32 v33, v33, s3, v2
	v_bfe_u32 v2, v38, 16, 1
	global_store_dwordx2 v[24:25], v[32:33], off
	v_add3_u32 v2, v38, v2, s13
	v_bfe_u32 v32, v39, 16, 1
	v_lshrrev_b32_e32 v2, 16, v2
	v_add3_u32 v32, v39, v32, s13
	v_and_or_b32 v32, v32, s3, v2
	v_bfe_u32 v2, v36, 16, 1
	v_add3_u32 v2, v36, v2, s13
	v_bfe_u32 v33, v37, 16, 1
	v_lshrrev_b32_e32 v2, 16, v2
	v_add3_u32 v33, v37, v33, s13
	v_and_or_b32 v33, v33, s3, v2
	v_bfe_u32 v2, v34, 16, 1
	global_store_dwordx2 v[24:25], v[32:33], off offset:512
	v_add3_u32 v2, v34, v2, s13
	v_bfe_u32 v32, v35, 16, 1
	v_lshrrev_b32_e32 v2, 16, v2
	v_add3_u32 v32, v35, v32, s13
	v_and_or_b32 v32, v32, s3, v2
	v_bfe_u32 v2, v30, 16, 1
	v_add3_u32 v2, v30, v2, s13
	v_bfe_u32 v33, v31, 16, 1
	v_lshrrev_b32_e32 v2, 16, v2
	v_add3_u32 v33, v31, v33, s13
	v_and_or_b32 v33, v33, s3, v2
	v_bfe_u32 v2, v28, 16, 1
	global_store_dwordx2 v[24:25], v[32:33], off offset:1024
	v_add3_u32 v2, v28, v2, s13
	v_bfe_u32 v32, v29, 16, 1
	v_lshrrev_b32_e32 v2, 16, v2
	v_add3_u32 v32, v29, v32, s13
	v_and_or_b32 v32, v32, s3, v2
	v_bfe_u32 v2, v26, 16, 1
	v_add3_u32 v2, v26, v2, s13
	v_bfe_u32 v33, v27, 16, 1
	v_lshrrev_b32_e32 v2, 16, v2
	v_add3_u32 v33, v27, v33, s13
	v_and_or_b32 v33, v33, s3, v2
	global_store_dwordx2 v[24:25], v[32:33], off offset:1536
	s_branch .LBB0_77

; __device__ __forceinline__ unsigned pk2(float lo, float hi) { return f2bf(lo) | (f2bf(hi) << 16); }
; template <bool FIRST, bool P8>
; __device__ __forceinline__ void phase_norm(Ctx& C, const float* nw, const float* w8src  , int ld8, int npart) {
;     ...
;         bf16* hrow = (bf16*)(C.ws + WS_H) + (size_t)m * D + 4 * lane;
;         f32x4 v[4]; float ss = 0.f;
;         if (FIRST) { const float* src = (m < MP ? C.in[0] + (size_t)m * D : C.in[1] + (size_t)(m - MP) * D);
; #pragma unroll
;             for (int j = 0; j < 4; ++j) v[j] = *(const f32x4*)(src + 4 * lane + 256 * j); }
;         else {
; #pragma unroll
;             for (int j = 0; j < 4; ++j) { const v2u hw = *(const v2u*)(hrow + 256 * j); v[j] = (f32x4){bflo(hw.x), bfhi(hw.x), bflo(hw.y), bfhi(hw.y)}; } }
;         if (!FIRST && m >= MP && npart > 0) {
;             const bf16* pp = (const bf16*)(C.ws + WS_PART) + (size_t)(m - MP) * D + 4 * lane;
;             for (int ks = 0; ks < npart; ++ks) {
; #pragma unroll
;                 for (int j = 0; j < 4; ++j) { const v2u pw = *(const v2u*)(pp + (size_t)ks * MS * D + 256 * j); v[j] += (f32x4){bflo(pw.x), bfhi(pw.x), bflo(pw.y), bfhi(pw.y)}; } }
; #pragma unroll
;             for (int j = 0; j < 4; ++j) { v2u hw; hw.x = pk2(v[j].x, v[j].y); hw.y = pk2(v[j].z, v[j].w); *(v2u*)(hrow + 256 * j) = hw; }
;         }
.LBB0_100:
	v_lshl_add_u64 v[150:151], s[22:23], 0, v[148:149]
	v_add_co_u32_e32 v152, vcc, 0x14300000, v150
	s_cmpk_lt_i32 s0, 0x4000
	s_nop 0
	v_addc_co_u32_e32 v153, vcc, 0, v151, vcc
	s_waitcnt lgkmcnt(6)
	global_load_dwordx2 v[154:155], v[152:153], off
	global_load_dwordx2 v[156:157], v[152:153], off offset:512
	s_waitcnt lgkmcnt(4)
	global_load_dwordx2 v[158:159], v[152:153], off offset:1024
	s_nop 0
	global_load_dwordx2 v[152:153], v[152:153], off offset:1536
	s_waitcnt vmcnt(3)
	v_lshlrev_b32_e32 v184, 16, v154
	v_and_b32_e32 v185, 0xffff0000, v154
	v_lshlrev_b32_e32 v186, 16, v155
	v_and_b32_e32 v187, 0xffff0000, v155
	s_waitcnt vmcnt(2) lgkmcnt(1)
	v_lshlrev_b32_e32 v180, 16, v156
	s_waitcnt lgkmcnt(0)
	v_and_b32_e32 v181, 0xffff0000, v156
	v_lshlrev_b32_e32 v182, 16, v157
	v_and_b32_e32 v183, 0xffff0000, v157
	s_waitcnt vmcnt(1)
	v_lshlrev_b32_e32 v162, 16, v158
	v_and_b32_e32 v163, 0xffff0000, v158
	v_lshlrev_b32_e32 v178, 16, v159
	v_and_b32_e32 v179, 0xffff0000, v159
	s_waitcnt vmcnt(0)
	v_lshlrev_b32_e32 v188, 16, v152
	v_and_b32_e32 v189, 0xffff0000, v152
	v_lshlrev_b32_e32 v190, 16, v153
	v_and_b32_e32 v191, 0xffff0000, v153
	s_cbranch_scc1 .LBB0_102
	s_mov_b64 s[4:5], 0x14300000
	v_lshl_add_u64 v[158:159], v[150:151], 0, s[4:5]
	s_mov_b64 s[4:5], 0x14300200
	v_lshl_add_u64 v[156:157], v[150:151], 0, s[4:5]
	s_mov_b64 s[4:5], 0x14300400
	v_lshl_add_u64 v[154:155], v[150:151], 0, s[4:5]
	s_mov_b64 s[4:5], 0x14300600
	s_add_i32 s84, s0, 0xffffc000
	v_lshl_add_u64 v[152:153], v[150:151], 0, s[4:5]
	s_lshl_b64 s[4:5], s[84:85], 11
	v_lshl_add_u64 v[160:161], v[0:1], 0, s[4:5]
	s_mov_b32 s4, 0x0
	s_mov_b32 s5, 0x0
	v_lshl_add_u64 v[204:205], v[160:161], 0, s[4:5]
	global_load_dwordx2 v[206:207], v[204:205], off
	global_load_dwordx2 v[208:209], v[204:205], off offset:512
	global_load_dwordx2 v[210:211], v[204:205], off offset:1024
	global_load_dwordx2 v[204:205], v[204:205], off offset:1536
	s_mov_b32 s4, 0x200000
	s_mov_b32 s5, 0x0
	v_lshl_add_u64 v[212:213], v[160:161], 0, s[4:5]
	global_load_dwordx2 v[214:215], v[212:213], off
	global_load_dwordx2 v[216:217], v[212:213], off offset:512
	global_load_dwordx2 v[218:219], v[212:213], off offset:1024
	global_load_dwordx2 v[212:213], v[212:213], off offset:1536
	s_mov_b32 s4, 0x400000
	s_mov_b32 s5, 0x0
	v_lshl_add_u64 v[220:221], v[160:161], 0, s[4:5]
	global_load_dwordx2 v[222:223], v[220:221], off
	global_load_dwordx2 v[224:225], v[220:221], off offset:512
	global_load_dwordx2 v[232:233], v[220:221], off offset:1024
	global_load_dwordx2 v[220:221], v[220:221], off offset:1536
	s_mov_b32 s4, 0x600000
	s_mov_b32 s5, 0x0
	v_lshl_add_u64 v[236:237], v[160:161], 0, s[4:5]
	global_load_dwordx2 v[242:243], v[236:237], off
	global_load_dwordx2 v[244:245], v[236:237], off offset:512
	global_load_dwordx2 v[246:247], v[236:237], off offset:1024
	global_load_dwordx2 v[236:237], v[236:237], off offset:1536
	s_waitcnt vmcnt(15)
	v_lshlrev_b32_e32 v200, 16, v206
	v_and_b32_e32 v201, 0xffff0000, v206
	v_lshlrev_b32_e32 v202, 16, v207
	v_and_b32_e32 v203, 0xffff0000, v207
	v_pk_add_f32 v[184:185], v[184:185], v[200:201]
	v_pk_add_f32 v[186:187], v[186:187], v[202:203]
	s_waitcnt vmcnt(14)
	v_lshlrev_b32_e32 v200, 16, v208
	v_and_b32_e32 v201, 0xffff0000, v208
	v_lshlrev_b32_e32 v202, 16, v209
	v_and_b32_e32 v203, 0xffff0000, v209
	v_pk_add_f32 v[180:181], v[180:181], v[200:201]
	v_pk_add_f32 v[182:183], v[182:183], v[202:203]
	s_waitcnt vmcnt(13)
	v_lshlrev_b32_e32 v200, 16, v210
	v_and_b32_e32 v201, 0xffff0000, v210
	v_lshlrev_b32_e32 v202, 16, v211
	v_and_b32_e32 v203, 0xffff0000, v211
	v_pk_add_f32 v[162:163], v[162:163], v[200:201]
	v_pk_add_f32 v[178:179], v[178:179], v[202:203]
	s_waitcnt vmcnt(12)
	v_lshlrev_b32_e32 v200, 16, v204
	v_and_b32_e32 v201, 0xffff0000, v204
	v_lshlrev_b32_e32 v202, 16, v205
	v_and_b32_e32 v203, 0xffff0000, v205
	v_pk_add_f32 v[188:189], v[188:189], v[200:201]
	v_pk_add_f32 v[190:191], v[190:191], v[202:203]
	s_waitcnt vmcnt(11)
	v_lshlrev_b32_e32 v200, 16, v214
	v_and_b32_e32 v201, 0xffff0000, v214
	v_lshlrev_b32_e32 v202, 16, v215
	v_and_b32_e32 v203, 0xffff0000, v215
	v_pk_add_f32 v[184:185], v[184:185], v[200:201]
	v_pk_add_f32 v[186:187], v[186:187], v[202:203]
	s_waitcnt vmcnt(10)
	v_lshlrev_b32_e32 v200, 16, v216
	v_and_b32_e32 v201, 0xffff0000, v216
	v_lshlrev_b32_e32 v202, 16, v217
	v_and_b32_e32 v203, 0xffff0000, v217
	v_pk_add_f32 v[180:181], v[180:181], v[200:201]
	v_pk_add_f32 v[182:183], v[182:183], v[202:203]
	s_waitcnt vmcnt(9)
	v_lshlrev_b32_e32 v200, 16, v218
	v_and_b32_e32 v201, 0xffff0000, v218
	v_lshlrev_b32_e32 v202, 16, v219
	v_and_b32_e32 v203, 0xffff0000, v219
	v_pk_add_f32 v[162:163], v[162:163], v[200:201]
	v_pk_add_f32 v[178:179], v[178:179], v[202:203]
	s_waitcnt vmcnt(8)
	v_lshlrev_b32_e32 v200, 16, v212
	v_and_b32_e32 v201, 0xffff0000, v212
	v_lshlrev_b32_e32 v202, 16, v213
	v_and_b32_e32 v203, 0xffff0000, v213
	v_pk_add_f32 v[188:189], v[188:189], v[200:201]
	v_pk_add_f32 v[190:191], v[190:191], v[202:203]
	s_waitcnt vmcnt(7)
	v_lshlrev_b32_e32 v200, 16, v222
	v_and_b32_e32 v201, 0xffff0000, v222
	v_lshlrev_b32_e32 v202, 16, v223
	v_and_b32_e32 v203, 0xffff0000, v223
	v_pk_add_f32 v[184:185], v[184:185], v[200:201]
	v_pk_add_f32 v[186:187], v[186:187], v[202:203]
	s_waitcnt vmcnt(6)
	v_lshlrev_b32_e32 v200, 16, v224
	v_and_b32_e32 v201, 0xffff0000, v224
	v_lshlrev_b32_e32 v202, 16, v225
	v_and_b32_e32 v203, 0xffff0000, v225
	v_pk_add_f32 v[180:181], v[180:181], v[200:201]
	v_pk_add_f32 v[182:183], v[182:183], v[202:203]
	s_waitcnt vmcnt(5)
; template <bool FIRST, bool P8>
; __device__ __forceinline__ void phase_norm(Ctx& C, const float* nw, const float* w8src  , int ld8, int npart) {
;     ...
;         if (!FIRST && m >= MP && npart > 0) {
;             const bf16* pp = (const bf16*)(C.ws + WS_PART) + (size_t)(m - MP) * D + 4 * lane;
;             for (int ks = 0; ks < npart; ++ks) {
; #pragma unroll
;                 for (int j = 0; j < 4; ++j) { const v2u pw = *(const v2u*)(pp + (size_t)ks * MS * D + 256 * j); v[j] += (f32x4){bflo(pw.x), bfhi(pw.x), bflo(pw.y), bfhi(pw.y)}; } }
	v_lshlrev_b32_e32 v200, 16, v232
	v_and_b32_e32 v201, 0xffff0000, v232
	v_lshlrev_b32_e32 v202, 16, v233
	v_and_b32_e32 v203, 0xffff0000, v233
	v_pk_add_f32 v[162:163], v[162:163], v[200:201]
	v_pk_add_f32 v[178:179], v[178:179], v[202:203]
	s_waitcnt vmcnt(4)
	v_lshlrev_b32_e32 v200, 16, v220
	v_and_b32_e32 v201, 0xffff0000, v220
	v_lshlrev_b32_e32 v202, 16, v221
	v_and_b32_e32 v203, 0xffff0000, v221
	v_pk_add_f32 v[188:189], v[188:189], v[200:201]
	v_pk_add_f32 v[190:191], v[190:191], v[202:203]
	s_waitcnt vmcnt(3)
	v_lshlrev_b32_e32 v200, 16, v242
	v_and_b32_e32 v201, 0xffff0000, v242
	v_lshlrev_b32_e32 v202, 16, v243
	v_and_b32_e32 v203, 0xffff0000, v243
	v_pk_add_f32 v[184:185], v[184:185], v[200:201]
	v_pk_add_f32 v[186:187], v[186:187], v[202:203]
	s_waitcnt vmcnt(2)
	v_lshlrev_b32_e32 v200, 16, v244
	v_and_b32_e32 v201, 0xffff0000, v244
	v_lshlrev_b32_e32 v202, 16, v245
	v_and_b32_e32 v203, 0xffff0000, v245
	v_pk_add_f32 v[180:181], v[180:181], v[200:201]
	v_pk_add_f32 v[182:183], v[182:183], v[202:203]
	s_waitcnt vmcnt(1)
	v_lshlrev_b32_e32 v200, 16, v246
	v_and_b32_e32 v201, 0xffff0000, v246
	v_lshlrev_b32_e32 v202, 16, v247
	v_and_b32_e32 v203, 0xffff0000, v247
	v_pk_add_f32 v[162:163], v[162:163], v[200:201]
	v_pk_add_f32 v[178:179], v[178:179], v[202:203]
	s_waitcnt vmcnt(0)
	v_lshlrev_b32_e32 v200, 16, v236
	v_and_b32_e32 v201, 0xffff0000, v236
	v_lshlrev_b32_e32 v202, 16, v237
	v_and_b32_e32 v203, 0xffff0000, v237
	v_pk_add_f32 v[188:189], v[188:189], v[200:201]
	v_pk_add_f32 v[190:191], v[190:191], v[202:203]
	s_mov_b32 s4, 0x800000
	s_mov_b32 s5, 0x0
	v_lshl_add_u64 v[204:205], v[160:161], 0, s[4:5]
	global_load_dwordx2 v[206:207], v[204:205], off
	global_load_dwordx2 v[208:209], v[204:205], off offset:512
	global_load_dwordx2 v[210:211], v[204:205], off offset:1024
	global_load_dwordx2 v[204:205], v[204:205], off offset:1536
	s_mov_b32 s4, 0xa00000
	s_mov_b32 s5, 0x0
	v_lshl_add_u64 v[212:213], v[160:161], 0, s[4:5]
	global_load_dwordx2 v[214:215], v[212:213], off
	global_load_dwordx2 v[216:217], v[212:213], off offset:512
	global_load_dwordx2 v[218:219], v[212:213], off offset:1024
	global_load_dwordx2 v[212:213], v[212:213], off offset:1536
	s_mov_b32 s4, 0xc00000
	s_mov_b32 s5, 0x0
	v_lshl_add_u64 v[220:221], v[160:161], 0, s[4:5]
	global_load_dwordx2 v[222:223], v[220:221], off
	global_load_dwordx2 v[224:225], v[220:221], off offset:512
	global_load_dwordx2 v[232:233], v[220:221], off offset:1024
	global_load_dwordx2 v[220:221], v[220:221], off offset:1536
	s_mov_b32 s4, 0xe00000
	s_mov_b32 s5, 0x0
	v_lshl_add_u64 v[236:237], v[160:161], 0, s[4:5]
	global_load_dwordx2 v[242:243], v[236:237], off
	global_load_dwordx2 v[244:245], v[236:237], off offset:512
	global_load_dwordx2 v[246:247], v[236:237], off offset:1024
	global_load_dwordx2 v[236:237], v[236:237], off offset:1536
	s_waitcnt vmcnt(15)
	v_lshlrev_b32_e32 v200, 16, v206
	v_and_b32_e32 v201, 0xffff0000, v206
	v_lshlrev_b32_e32 v202, 16, v207
	v_and_b32_e32 v203, 0xffff0000, v207
	v_pk_add_f32 v[184:185], v[184:185], v[200:201]
	v_pk_add_f32 v[186:187], v[186:187], v[202:203]
	s_waitcnt vmcnt(14)
	v_lshlrev_b32_e32 v200, 16, v208
	v_and_b32_e32 v201, 0xffff0000, v208
	v_lshlrev_b32_e32 v202, 16, v209
	v_and_b32_e32 v203, 0xffff0000, v209
	v_pk_add_f32 v[180:181], v[180:181], v[200:201]
	v_pk_add_f32 v[182:183], v[182:183], v[202:203]
	s_waitcnt vmcnt(13)
	v_lshlrev_b32_e32 v200, 16, v210
	v_and_b32_e32 v201, 0xffff0000, v210
	v_lshlrev_b32_e32 v202, 16, v211
	v_and_b32_e32 v203, 0xffff0000, v211
	v_pk_add_f32 v[162:163], v[162:163], v[200:201]
	v_pk_add_f32 v[178:179], v[178:179], v[202:203]
	s_waitcnt vmcnt(12)
	v_lshlrev_b32_e32 v200, 16, v204
	v_and_b32_e32 v201, 0xffff0000, v204
	v_lshlrev_b32_e32 v202, 16, v205
	v_and_b32_e32 v203, 0xffff0000, v205
	v_pk_add_f32 v[188:189], v[188:189], v[200:201]
	v_pk_add_f32 v[190:191], v[190:191], v[202:203]
	s_waitcnt vmcnt(11)
	v_lshlrev_b32_e32 v200, 16, v214
	v_and_b32_e32 v201, 0xffff0000, v214
	v_lshlrev_b32_e32 v202, 16, v215
	v_and_b32_e32 v203, 0xffff0000, v215
	v_pk_add_f32 v[184:185], v[184:185], v[200:201]
	v_pk_add_f32 v[186:187], v[186:187], v[202:203]
	s_waitcnt vmcnt(10)
	v_lshlrev_b32_e32 v200, 16, v216
	v_and_b32_e32 v201, 0xffff0000, v216
	v_lshlrev_b32_e32 v202, 16, v217
	v_and_b32_e32 v203, 0xffff0000, v217
	v_pk_add_f32 v[180:181], v[180:181], v[200:201]
	v_pk_add_f32 v[182:183], v[182:183], v[202:203]
	s_waitcnt vmcnt(9)
	v_lshlrev_b32_e32 v200, 16, v218
	v_and_b32_e32 v201, 0xffff0000, v218
	v_lshlrev_b32_e32 v202, 16, v219
	v_and_b32_e32 v203, 0xffff0000, v219
	v_pk_add_f32 v[162:163], v[162:163], v[200:201]
	v_pk_add_f32 v[178:179], v[178:179], v[202:203]
	s_waitcnt vmcnt(8)
	v_lshlrev_b32_e32 v200, 16, v212
	v_and_b32_e32 v201, 0xffff0000, v212
	v_lshlrev_b32_e32 v202, 16, v213
	v_and_b32_e32 v203, 0xffff0000, v213
	v_pk_add_f32 v[188:189], v[188:189], v[200:201]
	v_pk_add_f32 v[190:191], v[190:191], v[202:203]
	s_waitcnt vmcnt(7)
	v_lshlrev_b32_e32 v200, 16, v222
	v_and_b32_e32 v201, 0xffff0000, v222
	v_lshlrev_b32_e32 v202, 16, v223
	v_and_b32_e32 v203, 0xffff0000, v223
	v_pk_add_f32 v[184:185], v[184:185], v[200:201]
	v_pk_add_f32 v[186:187], v[186:187], v[202:203]
	s_waitcnt vmcnt(6)
	v_lshlrev_b32_e32 v200, 16, v224
	v_and_b32_e32 v201, 0xffff0000, v224
	v_lshlrev_b32_e32 v202, 16, v225
	v_and_b32_e32 v203, 0xffff0000, v225
	v_pk_add_f32 v[180:181], v[180:181], v[200:201]
	v_pk_add_f32 v[182:183], v[182:183], v[202:203]
	s_waitcnt vmcnt(5)
	v_lshlrev_b32_e32 v200, 16, v232
	v_and_b32_e32 v201, 0xffff0000, v232
	v_lshlrev_b32_e32 v202, 16, v233
	v_and_b32_e32 v203, 0xffff0000, v233
	v_pk_add_f32 v[162:163], v[162:163], v[200:201]
	v_pk_add_f32 v[178:179], v[178:179], v[202:203]
	s_waitcnt vmcnt(4)
; template <bool FIRST, bool P8>
; __device__ __forceinline__ void phase_norm(Ctx& C, const float* nw, const float* w8src  , int ld8, int npart) {
;     ...
;         if (!FIRST && m >= MP && npart > 0) {
;             const bf16* pp = (const bf16*)(C.ws + WS_PART) + (size_t)(m - MP) * D + 4 * lane;
;             for (int ks = 0; ks < npart; ++ks) {
; #pragma unroll
;                 for (int j = 0; j < 4; ++j) { const v2u pw = *(const v2u*)(pp + (size_t)ks * MS * D + 256 * j); v[j] += (f32x4){bflo(pw.x), bfhi(pw.x), bflo(pw.y), bfhi(pw.y)}; } }
	v_lshlrev_b32_e32 v200, 16, v220
	v_and_b32_e32 v201, 0xffff0000, v220
	v_lshlrev_b32_e32 v202, 16, v221
	v_and_b32_e32 v203, 0xffff0000, v221
	v_pk_add_f32 v[188:189], v[188:189], v[200:201]
	v_pk_add_f32 v[190:191], v[190:191], v[202:203]
	s_waitcnt vmcnt(3)
	v_lshlrev_b32_e32 v200, 16, v242
	v_and_b32_e32 v201, 0xffff0000, v242
	v_lshlrev_b32_e32 v202, 16, v243
	v_and_b32_e32 v203, 0xffff0000, v243
	v_pk_add_f32 v[184:185], v[184:185], v[200:201]
	v_pk_add_f32 v[186:187], v[186:187], v[202:203]
	s_waitcnt vmcnt(2)
	v_lshlrev_b32_e32 v200, 16, v244
	v_and_b32_e32 v201, 0xffff0000, v244
	v_lshlrev_b32_e32 v202, 16, v245
	v_and_b32_e32 v203, 0xffff0000, v245
	v_pk_add_f32 v[180:181], v[180:181], v[200:201]
	v_pk_add_f32 v[182:183], v[182:183], v[202:203]
	s_waitcnt vmcnt(1)
	v_lshlrev_b32_e32 v200, 16, v246
	v_and_b32_e32 v201, 0xffff0000, v246
	v_lshlrev_b32_e32 v202, 16, v247
	v_and_b32_e32 v203, 0xffff0000, v247
	v_pk_add_f32 v[162:163], v[162:163], v[200:201]
	v_pk_add_f32 v[178:179], v[178:179], v[202:203]
	s_waitcnt vmcnt(0)
	v_lshlrev_b32_e32 v200, 16, v236
	v_and_b32_e32 v201, 0xffff0000, v236
	v_lshlrev_b32_e32 v202, 16, v237
	v_and_b32_e32 v203, 0xffff0000, v237
	v_pk_add_f32 v[188:189], v[188:189], v[200:201]
	v_pk_add_f32 v[190:191], v[190:191], v[202:203]
	s_mov_b32 s4, 0x1000000
	s_mov_b32 s5, 0x0
	v_lshl_add_u64 v[204:205], v[160:161], 0, s[4:5]
	global_load_dwordx2 v[206:207], v[204:205], off
	global_load_dwordx2 v[208:209], v[204:205], off offset:512
	global_load_dwordx2 v[210:211], v[204:205], off offset:1024
	global_load_dwordx2 v[204:205], v[204:205], off offset:1536
	s_mov_b32 s4, 0x1200000
	s_mov_b32 s5, 0x0
	v_lshl_add_u64 v[212:213], v[160:161], 0, s[4:5]
	global_load_dwordx2 v[214:215], v[212:213], off
	global_load_dwordx2 v[216:217], v[212:213], off offset:512
	global_load_dwordx2 v[218:219], v[212:213], off offset:1024
	global_load_dwordx2 v[212:213], v[212:213], off offset:1536
	s_mov_b32 s4, 0x1400000
	s_mov_b32 s5, 0x0
	v_lshl_add_u64 v[220:221], v[160:161], 0, s[4:5]
	global_load_dwordx2 v[222:223], v[220:221], off
	global_load_dwordx2 v[224:225], v[220:221], off offset:512
	global_load_dwordx2 v[232:233], v[220:221], off offset:1024
	global_load_dwordx2 v[220:221], v[220:221], off offset:1536
	s_mov_b32 s4, 0x1600000
	s_mov_b32 s5, 0x0
	v_lshl_add_u64 v[236:237], v[160:161], 0, s[4:5]
	global_load_dwordx2 v[242:243], v[236:237], off
	global_load_dwordx2 v[244:245], v[236:237], off offset:512
	global_load_dwordx2 v[246:247], v[236:237], off offset:1024
	global_load_dwordx2 v[236:237], v[236:237], off offset:1536
	s_waitcnt vmcnt(15)
	v_lshlrev_b32_e32 v200, 16, v206
	v_and_b32_e32 v201, 0xffff0000, v206
	v_lshlrev_b32_e32 v202, 16, v207
	v_and_b32_e32 v203, 0xffff0000, v207
	v_pk_add_f32 v[184:185], v[184:185], v[200:201]
	v_pk_add_f32 v[186:187], v[186:187], v[202:203]
	s_waitcnt vmcnt(14)
	v_lshlrev_b32_e32 v200, 16, v208
	v_and_b32_e32 v201, 0xffff0000, v208
	v_lshlrev_b32_e32 v202, 16, v209
	v_and_b32_e32 v203, 0xffff0000, v209
	v_pk_add_f32 v[180:181], v[180:181], v[200:201]
	v_pk_add_f32 v[182:183], v[182:183], v[202:203]
	s_waitcnt vmcnt(13)
	v_lshlrev_b32_e32 v200, 16, v210
	v_and_b32_e32 v201, 0xffff0000, v210
	v_lshlrev_b32_e32 v202, 16, v211
	v_and_b32_e32 v203, 0xffff0000, v211
	v_pk_add_f32 v[162:163], v[162:163], v[200:201]
	v_pk_add_f32 v[178:179], v[178:179], v[202:203]
	s_waitcnt vmcnt(12)
	v_lshlrev_b32_e32 v200, 16, v204
	v_and_b32_e32 v201, 0xffff0000, v204
	v_lshlrev_b32_e32 v202, 16, v205
	v_and_b32_e32 v203, 0xffff0000, v205
	v_pk_add_f32 v[188:189], v[188:189], v[200:201]
	v_pk_add_f32 v[190:191], v[190:191], v[202:203]
	s_waitcnt vmcnt(11)
	v_lshlrev_b32_e32 v200, 16, v214
	v_and_b32_e32 v201, 0xffff0000, v214
	v_lshlrev_b32_e32 v202, 16, v215
	v_and_b32_e32 v203, 0xffff0000, v215
	v_pk_add_f32 v[184:185], v[184:185], v[200:201]
	v_pk_add_f32 v[186:187], v[186:187], v[202:203]
	s_waitcnt vmcnt(10)
	v_lshlrev_b32_e32 v200, 16, v216
	v_and_b32_e32 v201, 0xffff0000, v216
	v_lshlrev_b32_e32 v202, 16, v217
	v_and_b32_e32 v203, 0xffff0000, v217
	v_pk_add_f32 v[180:181], v[180:181], v[200:201]
	v_pk_add_f32 v[182:183], v[182:183], v[202:203]
	s_waitcnt vmcnt(9)
	v_lshlrev_b32_e32 v200, 16, v218
	v_and_b32_e32 v201, 0xffff0000, v218
	v_lshlrev_b32_e32 v202, 16, v219
	v_and_b32_e32 v203, 0xffff0000, v219
	v_pk_add_f32 v[162:163], v[162:163], v[200:201]
	v_pk_add_f32 v[178:179], v[178:179], v[202:203]
	s_waitcnt vmcnt(8)
	v_lshlrev_b32_e32 v200, 16, v212
	v_and_b32_e32 v201, 0xffff0000, v212
	v_lshlrev_b32_e32 v202, 16, v213
	v_and_b32_e32 v203, 0xffff0000, v213
	v_pk_add_f32 v[188:189], v[188:189], v[200:201]
	v_pk_add_f32 v[190:191], v[190:191], v[202:203]
	s_waitcnt vmcnt(7)
	v_lshlrev_b32_e32 v200, 16, v222
	v_and_b32_e32 v201, 0xffff0000, v222
	v_lshlrev_b32_e32 v202, 16, v223
	v_and_b32_e32 v203, 0xffff0000, v223
	v_pk_add_f32 v[184:185], v[184:185], v[200:201]
	v_pk_add_f32 v[186:187], v[186:187], v[202:203]
	s_waitcnt vmcnt(6)
	v_lshlrev_b32_e32 v200, 16, v224
	v_and_b32_e32 v201, 0xffff0000, v224
	v_lshlrev_b32_e32 v202, 16, v225
	v_and_b32_e32 v203, 0xffff0000, v225
	v_pk_add_f32 v[180:181], v[180:181], v[200:201]
	v_pk_add_f32 v[182:183], v[182:183], v[202:203]
	s_waitcnt vmcnt(5)
	v_lshlrev_b32_e32 v200, 16, v232
	v_and_b32_e32 v201, 0xffff0000, v232
	v_lshlrev_b32_e32 v202, 16, v233
	v_and_b32_e32 v203, 0xffff0000, v233
	v_pk_add_f32 v[162:163], v[162:163], v[200:201]
	v_pk_add_f32 v[178:179], v[178:179], v[202:203]
	s_waitcnt vmcnt(4)
	v_lshlrev_b32_e32 v200, 16, v220
	v_and_b32_e32 v201, 0xffff0000, v220
	v_lshlrev_b32_e32 v202, 16, v221
	v_and_b32_e32 v203, 0xffff0000, v221
	v_pk_add_f32 v[188:189], v[188:189], v[200:201]
	v_pk_add_f32 v[190:191], v[190:191], v[202:203]
	s_waitcnt vmcnt(3)
; template <bool FIRST, bool P8>
; __device__ __forceinline__ void phase_norm(Ctx& C, const float* nw, const float* w8src  , int ld8, int npart) {
;     ...
;         if (!FIRST && m >= MP && npart > 0) {
;             const bf16* pp = (const bf16*)(C.ws + WS_PART) + (size_t)(m - MP) * D + 4 * lane;
;             for (int ks = 0; ks < npart; ++ks) {
; #pragma unroll
;                 for (int j = 0; j < 4; ++j) { const v2u pw = *(const v2u*)(pp + (size_t)ks * MS * D + 256 * j); v[j] += (f32x4){bflo(pw.x), bfhi(pw.x), bflo(pw.y), bfhi(pw.y)}; } }
	v_lshlrev_b32_e32 v200, 16, v242
	v_and_b32_e32 v201, 0xffff0000, v242
	v_lshlrev_b32_e32 v202, 16, v243
	v_and_b32_e32 v203, 0xffff0000, v243
	v_pk_add_f32 v[184:185], v[184:185], v[200:201]
	v_pk_add_f32 v[186:187], v[186:187], v[202:203]
	s_waitcnt vmcnt(2)
	v_lshlrev_b32_e32 v200, 16, v244
	v_and_b32_e32 v201, 0xffff0000, v244
	v_lshlrev_b32_e32 v202, 16, v245
	v_and_b32_e32 v203, 0xffff0000, v245
	v_pk_add_f32 v[180:181], v[180:181], v[200:201]
	v_pk_add_f32 v[182:183], v[182:183], v[202:203]
	s_waitcnt vmcnt(1)
	v_lshlrev_b32_e32 v200, 16, v246
	v_and_b32_e32 v201, 0xffff0000, v246
	v_lshlrev_b32_e32 v202, 16, v247
	v_and_b32_e32 v203, 0xffff0000, v247
	v_pk_add_f32 v[162:163], v[162:163], v[200:201]
	v_pk_add_f32 v[178:179], v[178:179], v[202:203]
	s_waitcnt vmcnt(0)
	v_lshlrev_b32_e32 v200, 16, v236
	v_and_b32_e32 v201, 0xffff0000, v236
	v_lshlrev_b32_e32 v202, 16, v237
	v_and_b32_e32 v203, 0xffff0000, v237
	v_pk_add_f32 v[188:189], v[188:189], v[200:201]
	v_pk_add_f32 v[190:191], v[190:191], v[202:203]
	s_mov_b32 s4, 0x1800000
	s_mov_b32 s5, 0x0
	v_lshl_add_u64 v[204:205], v[160:161], 0, s[4:5]
	global_load_dwordx2 v[206:207], v[204:205], off
	global_load_dwordx2 v[208:209], v[204:205], off offset:512
	global_load_dwordx2 v[210:211], v[204:205], off offset:1024
	global_load_dwordx2 v[204:205], v[204:205], off offset:1536
	s_mov_b32 s4, 0x1a00000
	s_mov_b32 s5, 0x0
	v_lshl_add_u64 v[212:213], v[160:161], 0, s[4:5]
	global_load_dwordx2 v[214:215], v[212:213], off
	global_load_dwordx2 v[216:217], v[212:213], off offset:512
	global_load_dwordx2 v[218:219], v[212:213], off offset:1024
	global_load_dwordx2 v[212:213], v[212:213], off offset:1536
	s_mov_b32 s4, 0x1c00000
	s_mov_b32 s5, 0x0
	v_lshl_add_u64 v[220:221], v[160:161], 0, s[4:5]
	global_load_dwordx2 v[222:223], v[220:221], off
	global_load_dwordx2 v[224:225], v[220:221], off offset:512
	global_load_dwordx2 v[232:233], v[220:221], off offset:1024
	global_load_dwordx2 v[220:221], v[220:221], off offset:1536
	s_mov_b32 s4, 0x1e00000
	s_mov_b32 s5, 0x0
	v_lshl_add_u64 v[236:237], v[160:161], 0, s[4:5]
	global_load_dwordx2 v[242:243], v[236:237], off
	global_load_dwordx2 v[244:245], v[236:237], off offset:512
	global_load_dwordx2 v[246:247], v[236:237], off offset:1024
	global_load_dwordx2 v[236:237], v[236:237], off offset:1536
	s_waitcnt vmcnt(15)
	v_lshlrev_b32_e32 v200, 16, v206
	v_and_b32_e32 v201, 0xffff0000, v206
	v_lshlrev_b32_e32 v202, 16, v207
	v_and_b32_e32 v203, 0xffff0000, v207
	v_pk_add_f32 v[184:185], v[184:185], v[200:201]
	v_pk_add_f32 v[186:187], v[186:187], v[202:203]
	s_waitcnt vmcnt(14)
	v_lshlrev_b32_e32 v200, 16, v208
	v_and_b32_e32 v201, 0xffff0000, v208
	v_lshlrev_b32_e32 v202, 16, v209
	v_and_b32_e32 v203, 0xffff0000, v209
	v_pk_add_f32 v[180:181], v[180:181], v[200:201]
	v_pk_add_f32 v[182:183], v[182:183], v[202:203]
	s_waitcnt vmcnt(13)
	v_lshlrev_b32_e32 v200, 16, v210
	v_and_b32_e32 v201, 0xffff0000, v210
	v_lshlrev_b32_e32 v202, 16, v211
	v_and_b32_e32 v203, 0xffff0000, v211
	v_pk_add_f32 v[162:163], v[162:163], v[200:201]
	v_pk_add_f32 v[178:179], v[178:179], v[202:203]
	s_waitcnt vmcnt(12)
	v_lshlrev_b32_e32 v200, 16, v204
	v_and_b32_e32 v201, 0xffff0000, v204
	v_lshlrev_b32_e32 v202, 16, v205
	v_and_b32_e32 v203, 0xffff0000, v205
	v_pk_add_f32 v[188:189], v[188:189], v[200:201]
	v_pk_add_f32 v[190:191], v[190:191], v[202:203]
	s_waitcnt vmcnt(11)
	v_lshlrev_b32_e32 v200, 16, v214
	v_and_b32_e32 v201, 0xffff0000, v214
	v_lshlrev_b32_e32 v202, 16, v215
	v_and_b32_e32 v203, 0xffff0000, v215
	v_pk_add_f32 v[184:185], v[184:185], v[200:201]
	v_pk_add_f32 v[186:187], v[186:187], v[202:203]
	s_waitcnt vmcnt(10)
	v_lshlrev_b32_e32 v200, 16, v216
	v_and_b32_e32 v201, 0xffff0000, v216
	v_lshlrev_b32_e32 v202, 16, v217
	v_and_b32_e32 v203, 0xffff0000, v217
	v_pk_add_f32 v[180:181], v[180:181], v[200:201]
	v_pk_add_f32 v[182:183], v[182:183], v[202:203]
	s_waitcnt vmcnt(9)
	v_lshlrev_b32_e32 v200, 16, v218
	v_and_b32_e32 v201, 0xffff0000, v218
	v_lshlrev_b32_e32 v202, 16, v219
	v_and_b32_e32 v203, 0xffff0000, v219
	v_pk_add_f32 v[162:163], v[162:163], v[200:201]
	v_pk_add_f32 v[178:179], v[178:179], v[202:203]
	s_waitcnt vmcnt(8)
; __device__ __forceinline__ unsigned pk2(float lo, float hi) { return f2bf(lo) | (f2bf(hi) << 16); }
; template <bool FIRST, bool P8>
; __device__ __forceinline__ void phase_norm(Ctx& C, const float* nw, const float* w8src  , int ld8, int npart) {
;     ...
;         if (!FIRST && m >= MP && npart > 0) {
;             const bf16* pp = (const bf16*)(C.ws + WS_PART) + (size_t)(m - MP) * D + 4 * lane;
;             for (int ks = 0; ks < npart; ++ks) {
; #pragma unroll
;                 for (int j = 0; j < 4; ++j) { const v2u pw = *(const v2u*)(pp + (size_t)ks * MS * D + 256 * j); v[j] += (f32x4){bflo(pw.x), bfhi(pw.x), bflo(pw.y), bfhi(pw.y)}; } }
; #pragma unroll
;             for (int j = 0; j < 4; ++j) { v2u hw; hw.x = pk2(v[j].x, v[j].y); hw.y = pk2(v[j].z, v[j].w); *(v2u*)(hrow + 256 * j) = hw; }
;         }
	v_lshlrev_b32_e32 v200, 16, v212
	v_and_b32_e32 v201, 0xffff0000, v212
	v_lshlrev_b32_e32 v202, 16, v213
	v_and_b32_e32 v203, 0xffff0000, v213
	v_pk_add_f32 v[188:189], v[188:189], v[200:201]
	v_pk_add_f32 v[190:191], v[190:191], v[202:203]
	s_waitcnt vmcnt(7)
	v_lshlrev_b32_e32 v200, 16, v222
	v_and_b32_e32 v201, 0xffff0000, v222
	v_lshlrev_b32_e32 v202, 16, v223
	v_and_b32_e32 v203, 0xffff0000, v223
	v_pk_add_f32 v[184:185], v[184:185], v[200:201]
	v_pk_add_f32 v[186:187], v[186:187], v[202:203]
	s_waitcnt vmcnt(6)
	v_lshlrev_b32_e32 v200, 16, v224
	v_and_b32_e32 v201, 0xffff0000, v224
	v_lshlrev_b32_e32 v202, 16, v225
	v_and_b32_e32 v203, 0xffff0000, v225
	v_pk_add_f32 v[180:181], v[180:181], v[200:201]
	v_pk_add_f32 v[182:183], v[182:183], v[202:203]
	s_waitcnt vmcnt(5)
	v_lshlrev_b32_e32 v200, 16, v232
	v_and_b32_e32 v201, 0xffff0000, v232
	v_lshlrev_b32_e32 v202, 16, v233
	v_and_b32_e32 v203, 0xffff0000, v233
	v_pk_add_f32 v[162:163], v[162:163], v[200:201]
	v_pk_add_f32 v[178:179], v[178:179], v[202:203]
	s_waitcnt vmcnt(4)
	v_lshlrev_b32_e32 v200, 16, v220
	v_and_b32_e32 v201, 0xffff0000, v220
	v_lshlrev_b32_e32 v202, 16, v221
	v_and_b32_e32 v203, 0xffff0000, v221
	v_pk_add_f32 v[188:189], v[188:189], v[200:201]
	v_pk_add_f32 v[190:191], v[190:191], v[202:203]
	s_waitcnt vmcnt(3)
	v_lshlrev_b32_e32 v200, 16, v242
	v_and_b32_e32 v201, 0xffff0000, v242
	v_lshlrev_b32_e32 v202, 16, v243
	v_and_b32_e32 v203, 0xffff0000, v243
	v_pk_add_f32 v[184:185], v[184:185], v[200:201]
	v_pk_add_f32 v[186:187], v[186:187], v[202:203]
	s_waitcnt vmcnt(2)
	v_lshlrev_b32_e32 v200, 16, v244
	v_and_b32_e32 v201, 0xffff0000, v244
	v_lshlrev_b32_e32 v202, 16, v245
	v_and_b32_e32 v203, 0xffff0000, v245
	v_pk_add_f32 v[180:181], v[180:181], v[200:201]
	v_pk_add_f32 v[182:183], v[182:183], v[202:203]
	s_waitcnt vmcnt(1)
	v_lshlrev_b32_e32 v200, 16, v246
	v_and_b32_e32 v201, 0xffff0000, v246
	v_lshlrev_b32_e32 v202, 16, v247
	v_and_b32_e32 v203, 0xffff0000, v247
	v_pk_add_f32 v[162:163], v[162:163], v[200:201]
	v_pk_add_f32 v[178:179], v[178:179], v[202:203]
	s_waitcnt vmcnt(0)
	v_lshlrev_b32_e32 v200, 16, v236
	v_and_b32_e32 v201, 0xffff0000, v236
	v_lshlrev_b32_e32 v202, 16, v237
	v_and_b32_e32 v203, 0xffff0000, v237
	v_pk_add_f32 v[188:189], v[188:189], v[200:201]
	v_pk_add_f32 v[190:191], v[190:191], v[202:203]
	v_bfe_u32 v200, v184, 16, 1
	v_add3_u32 v200, v184, v200, s13
	v_lshrrev_b32_e32 v200, 16, v200
	v_bfe_u32 v201, v185, 16, 1
	v_add3_u32 v201, v185, v201, s13
	v_and_or_b32 v202, v201, s3, v200
	v_bfe_u32 v200, v186, 16, 1
	v_add3_u32 v200, v186, v200, s13
	v_lshrrev_b32_e32 v200, 16, v200
	v_bfe_u32 v201, v187, 16, 1
	v_add3_u32 v201, v187, v201, s13
	v_and_or_b32 v203, v201, s3, v200
	global_store_dwordx2 v[158:159], v[202:203], off
	v_bfe_u32 v200, v180, 16, 1
	v_add3_u32 v200, v180, v200, s13
	v_lshrrev_b32_e32 v200, 16, v200
	v_bfe_u32 v201, v181, 16, 1
	v_add3_u32 v201, v181, v201, s13
	v_and_or_b32 v202, v201, s3, v200
	v_bfe_u32 v200, v182, 16, 1
	v_add3_u32 v200, v182, v200, s13
	v_lshrrev_b32_e32 v200, 16, v200
	v_bfe_u32 v201, v183, 16, 1
	v_add3_u32 v201, v183, v201, s13
	v_and_or_b32 v203, v201, s3, v200
	global_store_dwordx2 v[156:157], v[202:203], off
	v_bfe_u32 v200, v162, 16, 1
	v_add3_u32 v200, v162, v200, s13
	v_lshrrev_b32_e32 v200, 16, v200
	v_bfe_u32 v201, v163, 16, 1
	v_add3_u32 v201, v163, v201, s13
	v_and_or_b32 v202, v201, s3, v200
	v_bfe_u32 v200, v178, 16, 1
	v_add3_u32 v200, v178, v200, s13
	v_lshrrev_b32_e32 v200, 16, v200
	v_bfe_u32 v201, v179, 16, 1
	v_add3_u32 v201, v179, v201, s13
	v_and_or_b32 v203, v201, s3, v200
	global_store_dwordx2 v[154:155], v[202:203], off
	v_bfe_u32 v200, v188, 16, 1
	v_add3_u32 v200, v188, v200, s13
	v_lshrrev_b32_e32 v200, 16, v200
	v_bfe_u32 v201, v189, 16, 1
	v_add3_u32 v201, v189, v201, s13
	v_and_or_b32 v202, v201, s3, v200
	v_bfe_u32 v200, v190, 16, 1
	v_add3_u32 v200, v190, v200, s13
	v_lshrrev_b32_e32 v200, 16, v200
	v_bfe_u32 v201, v191, 16, 1
	v_add3_u32 v201, v191, v201, s13
	v_and_or_b32 v203, v201, s3, v200
	global_store_dwordx2 v[152:153], v[202:203], off
	s_mov_b32 s2, 0x1c00000
	s_branch .LBB0_103

; template <bool FIRST, bool P8>
; __device__ __forceinline__ void phase_norm(Ctx& C, const float* nw, const float* w8src  , int ld8, int npart) {
;     ...
;             for (int j = 0; j < 4; ++j) { const v2u hw = *(const v2u*)(hrow + 256 * j); v[j] = (f32x4){bflo(hw.x), bfhi(hw.x), bflo(hw.y), bfhi(hw.y)}; } }
;         if (!FIRST && m >= MP && npart > 0) {
.LBB0_1708:
	global_load_dwordx2 v[22:23], v[20:21], off
	global_load_dwordx2 v[24:25], v[20:21], off offset:512
	global_load_dwordx2 v[34:35], v[20:21], off offset:1024
	global_load_dwordx2 v[36:37], v[20:21], off offset:1536
	s_cmpk_lt_i32 s0, 0x4000
	s_waitcnt vmcnt(3)
	v_lshlrev_b32_e32 v32, 16, v22
	v_and_b32_e32 v33, 0xffff0000, v22
	v_lshlrev_b32_e32 v30, 16, v23
	v_and_b32_e32 v31, 0xffff0000, v23
	s_waitcnt vmcnt(2)
	v_lshlrev_b32_e32 v28, 16, v24
	v_and_b32_e32 v29, 0xffff0000, v24
	v_lshlrev_b32_e32 v26, 16, v25
	v_and_b32_e32 v27, 0xffff0000, v25
	s_waitcnt vmcnt(1)
	v_lshlrev_b32_e32 v24, 16, v34
	v_and_b32_e32 v25, 0xffff0000, v34
	v_lshlrev_b32_e32 v22, 16, v35
	v_and_b32_e32 v23, 0xffff0000, v35
	s_waitcnt vmcnt(0)
	v_lshlrev_b32_e32 v34, 16, v36
	v_and_b32_e32 v35, 0xffff0000, v36
	v_lshlrev_b32_e32 v36, 16, v37
	v_and_b32_e32 v37, 0xffff0000, v37
	s_cbranch_scc1 .LBB0_1707
; __device__ __forceinline__ unsigned pk2(float lo, float hi) { return f2bf(lo) | (f2bf(hi) << 16); }
; template <bool FIRST, bool P8>
; __device__ __forceinline__ void phase_norm(Ctx& C, const float* nw, const float* w8src  , int ld8, int npart) {
;     ...
;         if (!FIRST && m >= MP && npart > 0) {
;             const bf16* pp = (const bf16*)(C.ws + WS_PART) + (size_t)(m - MP) * D + 4 * lane;
;             for (int ks = 0; ks < npart; ++ks) {
; #pragma unroll
;                 for (int j = 0; j < 4; ++j) { const v2u pw = *(const v2u*)(pp + (size_t)ks * MS * D + 256 * j); v[j] += (f32x4){bflo(pw.x), bfhi(pw.x), bflo(pw.y), bfhi(pw.y)}; } }
; #pragma unroll
;             for (int j = 0; j < 4; ++j) { v2u hw; hw.x = pk2(v[j].x, v[j].y); hw.y = pk2(v[j].z, v[j].w); *(v2u*)(hrow + 256 * j) = hw; }
;         }
	s_add_i32 s84, s0, 0xffffc000
	s_lshl_b64 s[4:5], s[84:85], 11
	v_lshl_add_u64 v[38:39], v[0:1], 0, s[4:5]
	s_mov_b32 s4, 0x0
	s_mov_b32 s5, 0x0
	v_lshl_add_u64 v[58:59], v[38:39], 0, s[4:5]
	global_load_dwordx2 v[60:61], v[58:59], off
	global_load_dwordx2 v[62:63], v[58:59], off offset:512
	global_load_dwordx2 v[64:65], v[58:59], off offset:1024
	global_load_dwordx2 v[58:59], v[58:59], off offset:1536
	s_mov_b32 s4, 0x200000
	s_mov_b32 s5, 0x0
	v_lshl_add_u64 v[66:67], v[38:39], 0, s[4:5]
	global_load_dwordx2 v[68:69], v[66:67], off
	global_load_dwordx2 v[70:71], v[66:67], off offset:512
	global_load_dwordx2 v[72:73], v[66:67], off offset:1024
	global_load_dwordx2 v[66:67], v[66:67], off offset:1536
	s_mov_b32 s4, 0x400000
	s_mov_b32 s5, 0x0
	v_lshl_add_u64 v[74:75], v[38:39], 0, s[4:5]
	global_load_dwordx2 v[76:77], v[74:75], off
	global_load_dwordx2 v[78:79], v[74:75], off offset:512
	global_load_dwordx2 v[80:81], v[74:75], off offset:1024
	global_load_dwordx2 v[74:75], v[74:75], off offset:1536
	s_mov_b32 s4, 0x600000
	s_mov_b32 s5, 0x0
	v_lshl_add_u64 v[82:83], v[38:39], 0, s[4:5]
	global_load_dwordx2 v[84:85], v[82:83], off
	global_load_dwordx2 v[86:87], v[82:83], off offset:512
	global_load_dwordx2 v[88:89], v[82:83], off offset:1024
	global_load_dwordx2 v[82:83], v[82:83], off offset:1536
	s_waitcnt vmcnt(15)
	v_lshlrev_b32_e32 v54, 16, v60
	v_and_b32_e32 v55, 0xffff0000, v60
	v_lshlrev_b32_e32 v56, 16, v61
	v_and_b32_e32 v57, 0xffff0000, v61
	v_pk_add_f32 v[32:33], v[32:33], v[54:55]
	v_pk_add_f32 v[30:31], v[30:31], v[56:57]
	s_waitcnt vmcnt(14)
	v_lshlrev_b32_e32 v54, 16, v62
	v_and_b32_e32 v55, 0xffff0000, v62
	v_lshlrev_b32_e32 v56, 16, v63
	v_and_b32_e32 v57, 0xffff0000, v63
	v_pk_add_f32 v[28:29], v[28:29], v[54:55]
	v_pk_add_f32 v[26:27], v[26:27], v[56:57]
	s_waitcnt vmcnt(13)
	v_lshlrev_b32_e32 v54, 16, v64
	v_and_b32_e32 v55, 0xffff0000, v64
	v_lshlrev_b32_e32 v56, 16, v65
	v_and_b32_e32 v57, 0xffff0000, v65
	v_pk_add_f32 v[24:25], v[24:25], v[54:55]
	v_pk_add_f32 v[22:23], v[22:23], v[56:57]
	s_waitcnt vmcnt(12)
	v_lshlrev_b32_e32 v54, 16, v58
	v_and_b32_e32 v55, 0xffff0000, v58
	v_lshlrev_b32_e32 v56, 16, v59
	v_and_b32_e32 v57, 0xffff0000, v59
	v_pk_add_f32 v[34:35], v[34:35], v[54:55]
	v_pk_add_f32 v[36:37], v[36:37], v[56:57]
	s_waitcnt vmcnt(11)
	v_lshlrev_b32_e32 v54, 16, v68
	v_and_b32_e32 v55, 0xffff0000, v68
	v_lshlrev_b32_e32 v56, 16, v69
	v_and_b32_e32 v57, 0xffff0000, v69
	v_pk_add_f32 v[32:33], v[32:33], v[54:55]
	v_pk_add_f32 v[30:31], v[30:31], v[56:57]
	s_waitcnt vmcnt(10)
	v_lshlrev_b32_e32 v54, 16, v70
	v_and_b32_e32 v55, 0xffff0000, v70
	v_lshlrev_b32_e32 v56, 16, v71
	v_and_b32_e32 v57, 0xffff0000, v71
	v_pk_add_f32 v[28:29], v[28:29], v[54:55]
	v_pk_add_f32 v[26:27], v[26:27], v[56:57]
	s_waitcnt vmcnt(9)
	v_lshlrev_b32_e32 v54, 16, v72
	v_and_b32_e32 v55, 0xffff0000, v72
	v_lshlrev_b32_e32 v56, 16, v73
	v_and_b32_e32 v57, 0xffff0000, v73
	v_pk_add_f32 v[24:25], v[24:25], v[54:55]
	v_pk_add_f32 v[22:23], v[22:23], v[56:57]
	s_waitcnt vmcnt(8)
	v_lshlrev_b32_e32 v54, 16, v66
	v_and_b32_e32 v55, 0xffff0000, v66
	v_lshlrev_b32_e32 v56, 16, v67
	v_and_b32_e32 v57, 0xffff0000, v67
	v_pk_add_f32 v[34:35], v[34:35], v[54:55]
	v_pk_add_f32 v[36:37], v[36:37], v[56:57]
	s_waitcnt vmcnt(7)
	v_lshlrev_b32_e32 v54, 16, v76
	v_and_b32_e32 v55, 0xffff0000, v76
	v_lshlrev_b32_e32 v56, 16, v77
	v_and_b32_e32 v57, 0xffff0000, v77
	v_pk_add_f32 v[32:33], v[32:33], v[54:55]
	v_pk_add_f32 v[30:31], v[30:31], v[56:57]
	s_waitcnt vmcnt(6)
	v_lshlrev_b32_e32 v54, 16, v78
	v_and_b32_e32 v55, 0xffff0000, v78
	v_lshlrev_b32_e32 v56, 16, v79
	v_and_b32_e32 v57, 0xffff0000, v79
	v_pk_add_f32 v[28:29], v[28:29], v[54:55]
	v_pk_add_f32 v[26:27], v[26:27], v[56:57]
	s_waitcnt vmcnt(5)
	v_lshlrev_b32_e32 v54, 16, v80
	v_and_b32_e32 v55, 0xffff0000, v80
	v_lshlrev_b32_e32 v56, 16, v81
	v_and_b32_e32 v57, 0xffff0000, v81
	v_pk_add_f32 v[24:25], v[24:25], v[54:55]
	v_pk_add_f32 v[22:23], v[22:23], v[56:57]
	s_waitcnt vmcnt(4)
	v_lshlrev_b32_e32 v54, 16, v74
	v_and_b32_e32 v55, 0xffff0000, v74
	v_lshlrev_b32_e32 v56, 16, v75
	v_and_b32_e32 v57, 0xffff0000, v75
	v_pk_add_f32 v[34:35], v[34:35], v[54:55]
	v_pk_add_f32 v[36:37], v[36:37], v[56:57]
	s_waitcnt vmcnt(3)
	v_lshlrev_b32_e32 v54, 16, v84
	v_and_b32_e32 v55, 0xffff0000, v84
	v_lshlrev_b32_e32 v56, 16, v85
	v_and_b32_e32 v57, 0xffff0000, v85
	v_pk_add_f32 v[32:33], v[32:33], v[54:55]
	v_pk_add_f32 v[30:31], v[30:31], v[56:57]
	s_waitcnt vmcnt(2)
	v_lshlrev_b32_e32 v54, 16, v86
	v_and_b32_e32 v55, 0xffff0000, v86
	v_lshlrev_b32_e32 v56, 16, v87
	v_and_b32_e32 v57, 0xffff0000, v87
	v_pk_add_f32 v[28:29], v[28:29], v[54:55]
	v_pk_add_f32 v[26:27], v[26:27], v[56:57]
	s_waitcnt vmcnt(1)
	v_lshlrev_b32_e32 v54, 16, v88
	v_and_b32_e32 v55, 0xffff0000, v88
	v_lshlrev_b32_e32 v56, 16, v89
	v_and_b32_e32 v57, 0xffff0000, v89
	v_pk_add_f32 v[24:25], v[24:25], v[54:55]
	v_pk_add_f32 v[22:23], v[22:23], v[56:57]
	s_waitcnt vmcnt(0)
	v_lshlrev_b32_e32 v54, 16, v82
	v_and_b32_e32 v55, 0xffff0000, v82
	v_lshlrev_b32_e32 v56, 16, v83
	v_and_b32_e32 v57, 0xffff0000, v83
	v_pk_add_f32 v[34:35], v[34:35], v[54:55]
	v_pk_add_f32 v[36:37], v[36:37], v[56:57]
	v_bfe_u32 v54, v32, 16, 1
	v_add3_u32 v54, v32, v54, s13
	v_lshrrev_b32_e32 v54, 16, v54
	v_bfe_u32 v55, v33, 16, 1
	v_add3_u32 v55, v33, v55, s13
	v_and_or_b32 v56, v55, s3, v54
	v_bfe_u32 v54, v30, 16, 1
	v_add3_u32 v54, v30, v54, s13
	v_lshrrev_b32_e32 v54, 16, v54
	v_bfe_u32 v55, v31, 16, 1
	v_add3_u32 v55, v31, v55, s13
	v_and_or_b32 v57, v55, s3, v54
	global_store_dwordx2 v[20:21], v[56:57], off
	v_bfe_u32 v54, v28, 16, 1
	v_add3_u32 v54, v28, v54, s13
	v_lshrrev_b32_e32 v54, 16, v54
	v_bfe_u32 v55, v29, 16, 1
	v_add3_u32 v55, v29, v55, s13
	v_and_or_b32 v56, v55, s3, v54
	v_bfe_u32 v54, v26, 16, 1
	v_add3_u32 v54, v26, v54, s13
	v_lshrrev_b32_e32 v54, 16, v54
	v_bfe_u32 v55, v27, 16, 1
	v_add3_u32 v55, v27, v55, s13
	v_and_or_b32 v57, v55, s3, v54
	global_store_dwordx2 v[20:21], v[56:57], off offset:512
	v_bfe_u32 v54, v24, 16, 1
	v_add3_u32 v54, v24, v54, s13
	v_lshrrev_b32_e32 v54, 16, v54
	v_bfe_u32 v55, v25, 16, 1
	v_add3_u32 v55, v25, v55, s13
	v_and_or_b32 v56, v55, s3, v54
	v_bfe_u32 v54, v22, 16, 1
	v_add3_u32 v54, v22, v54, s13
	v_lshrrev_b32_e32 v54, 16, v54
	v_bfe_u32 v55, v23, 16, 1
	v_add3_u32 v55, v23, v55, s13
	v_and_or_b32 v57, v55, s3, v54
	global_store_dwordx2 v[20:21], v[56:57], off offset:1024
	v_bfe_u32 v54, v34, 16, 1
	v_add3_u32 v54, v34, v54, s13
	v_lshrrev_b32_e32 v54, 16, v54
	v_bfe_u32 v55, v35, 16, 1
	v_add3_u32 v55, v35, v55, s13
	v_and_or_b32 v56, v55, s3, v54
	v_bfe_u32 v54, v36, 16, 1
	v_add3_u32 v54, v36, v54, s13
	v_lshrrev_b32_e32 v54, 16, v54
	v_bfe_u32 v55, v37, 16, 1
	v_add3_u32 v55, v37, v55, s13
	v_and_or_b32 v57, v55, s3, v54
	global_store_dwordx2 v[20:21], v[56:57], off offset:1536
	s_branch .LBB0_1707

; __device__ __forceinline__ void phase_final(Ctx& C) {
;     ...
;         float* row = C.out + (size_t)m * D; f32x4 v[4]; float ss = 0.f; const bf16* hrow = (const bf16*)(C.ws + WS_H) + (size_t)m * D + 4 * lane;
; #pragma unroll
;         for (int j = 0; j < 4; ++j) { const v2u hw = *(const v2u*)(hrow + 256 * j); v[j] = (f32x4){bflo(hw.x), bfhi(hw.x), bflo(hw.y), bfhi(hw.y)}; }
;         if (m >= MP) { const bf16* pp = (const bf16*)(C.ws + WS_PART) + (size_t)(m - MP) * D + 4 * lane;
;             for (int ks = 0; ks < 16; ++ks) {
; #pragma unroll
;                 for (int j = 0; j < 4; ++j) { const v2u pw = *(const v2u*)(pp + (size_t)ks * MS * D + 256 * j); v[j] += (f32x4){bflo(pw.x), bfhi(pw.x), bflo(pw.y), bfhi(pw.y)}; } } }
.LBB0_2118:
	global_load_dwordx2 v[22:23], v[20:21], off offset:-1024
	global_load_dwordx2 v[28:29], v[20:21], off offset:-512
	global_load_dwordx2 v[32:33], v[20:21], off
	global_load_dwordx2 v[38:39], v[20:21], off offset:512
	s_cmpk_lt_i32 s2, 0x4000
	s_waitcnt vmcnt(3)
	v_lshlrev_b32_e32 v26, 16, v22
	v_and_b32_e32 v27, 0xffff0000, v22
	v_lshlrev_b32_e32 v24, 16, v23
	v_and_b32_e32 v25, 0xffff0000, v23
	s_waitcnt vmcnt(2)
	v_lshlrev_b32_e32 v30, 16, v28
	v_and_b32_e32 v31, 0xffff0000, v28
	v_lshlrev_b32_e32 v28, 16, v29
	v_and_b32_e32 v29, 0xffff0000, v29
	s_waitcnt vmcnt(1)
	v_lshlrev_b32_e32 v34, 16, v32
	v_and_b32_e32 v35, 0xffff0000, v32
	v_lshlrev_b32_e32 v32, 16, v33
	v_and_b32_e32 v33, 0xffff0000, v33
	s_waitcnt vmcnt(0)
	v_lshlrev_b32_e32 v36, 16, v38
	v_and_b32_e32 v37, 0xffff0000, v38
	v_lshlrev_b32_e32 v38, 16, v39
	v_and_b32_e32 v39, 0xffff0000, v39
	s_cbranch_scc1 .LBB0_2117
	s_add_i32 s0, s2, 0xffffc000
	s_lshl_b64 s[16:17], s[0:1], 11
	v_lshl_add_u64 v[22:23], v[16:17], 0, s[16:17]
	s_mov_b32 s16, 0x0
	s_mov_b32 s17, 0x0
	v_lshl_add_u64 v[62:63], v[22:23], 0, s[16:17]
	global_load_dwordx2 v[64:65], v[62:63], off
	global_load_dwordx2 v[66:67], v[62:63], off offset:512
	global_load_dwordx2 v[68:69], v[62:63], off offset:1024
	global_load_dwordx2 v[62:63], v[62:63], off offset:1536
	s_mov_b32 s16, 0x200000
	s_mov_b32 s17, 0x0
	v_lshl_add_u64 v[70:71], v[22:23], 0, s[16:17]
	global_load_dwordx2 v[72:73], v[70:71], off
	global_load_dwordx2 v[74:75], v[70:71], off offset:512
	global_load_dwordx2 v[76:77], v[70:71], off offset:1024
	global_load_dwordx2 v[70:71], v[70:71], off offset:1536
	s_mov_b32 s16, 0x400000
	s_mov_b32 s17, 0x0
	v_lshl_add_u64 v[78:79], v[22:23], 0, s[16:17]
	global_load_dwordx2 v[80:81], v[78:79], off
	global_load_dwordx2 v[82:83], v[78:79], off offset:512
	global_load_dwordx2 v[84:85], v[78:79], off offset:1024
	global_load_dwordx2 v[78:79], v[78:79], off offset:1536
	s_mov_b32 s16, 0x600000
	s_mov_b32 s17, 0x0
	v_lshl_add_u64 v[86:87], v[22:23], 0, s[16:17]
	global_load_dwordx2 v[88:89], v[86:87], off
	global_load_dwordx2 v[90:91], v[86:87], off offset:512
	global_load_dwordx2 v[92:93], v[86:87], off offset:1024
	global_load_dwordx2 v[86:87], v[86:87], off offset:1536
	s_mov_b32 s16, 0x800000
	s_mov_b32 s17, 0x0
	v_lshl_add_u64 v[94:95], v[22:23], 0, s[16:17]
	global_load_dwordx2 v[96:97], v[94:95], off
	global_load_dwordx2 v[98:99], v[94:95], off offset:512
	global_load_dwordx2 v[100:101], v[94:95], off offset:1024
	global_load_dwordx2 v[94:95], v[94:95], off offset:1536
	s_mov_b32 s16, 0xa00000
	s_mov_b32 s17, 0x0
	v_lshl_add_u64 v[102:103], v[22:23], 0, s[16:17]
	global_load_dwordx2 v[104:105], v[102:103], off
	global_load_dwordx2 v[106:107], v[102:103], off offset:512
	global_load_dwordx2 v[108:109], v[102:103], off offset:1024
	global_load_dwordx2 v[102:103], v[102:103], off offset:1536
	s_mov_b32 s16, 0xc00000
	s_mov_b32 s17, 0x0
	v_lshl_add_u64 v[110:111], v[22:23], 0, s[16:17]
	global_load_dwordx2 v[112:113], v[110:111], off
	global_load_dwordx2 v[114:115], v[110:111], off offset:512
	global_load_dwordx2 v[116:117], v[110:111], off offset:1024
	global_load_dwordx2 v[110:111], v[110:111], off offset:1536
	s_mov_b32 s16, 0xe00000
	s_mov_b32 s17, 0x0
	v_lshl_add_u64 v[118:119], v[22:23], 0, s[16:17]
	global_load_dwordx2 v[120:121], v[118:119], off
	global_load_dwordx2 v[122:123], v[118:119], off offset:512
	global_load_dwordx2 v[124:125], v[118:119], off offset:1024
	global_load_dwordx2 v[118:119], v[118:119], off offset:1536
	s_waitcnt vmcnt(31)
	v_lshlrev_b32_e32 v58, 16, v64
	v_and_b32_e32 v59, 0xffff0000, v64
	v_lshlrev_b32_e32 v60, 16, v65
	v_and_b32_e32 v61, 0xffff0000, v65
	v_pk_add_f32 v[26:27], v[26:27], v[58:59]
	v_pk_add_f32 v[24:25], v[24:25], v[60:61]
	s_waitcnt vmcnt(30)
	v_lshlrev_b32_e32 v58, 16, v66
	v_and_b32_e32 v59, 0xffff0000, v66
	v_lshlrev_b32_e32 v60, 16, v67
	v_and_b32_e32 v61, 0xffff0000, v67
	v_pk_add_f32 v[30:31], v[30:31], v[58:59]
	v_pk_add_f32 v[28:29], v[28:29], v[60:61]
	s_waitcnt vmcnt(29)
	v_lshlrev_b32_e32 v58, 16, v68
	v_and_b32_e32 v59, 0xffff0000, v68
	v_lshlrev_b32_e32 v60, 16, v69
	v_and_b32_e32 v61, 0xffff0000, v69
	v_pk_add_f32 v[34:35], v[34:35], v[58:59]
	v_pk_add_f32 v[32:33], v[32:33], v[60:61]
	s_waitcnt vmcnt(28)
	v_lshlrev_b32_e32 v58, 16, v62
	v_and_b32_e32 v59, 0xffff0000, v62
	v_lshlrev_b32_e32 v60, 16, v63
	v_and_b32_e32 v61, 0xffff0000, v63
	v_pk_add_f32 v[36:37], v[36:37], v[58:59]
	v_pk_add_f32 v[38:39], v[38:39], v[60:61]
	s_waitcnt vmcnt(27)
	v_lshlrev_b32_e32 v58, 16, v72
	v_and_b32_e32 v59, 0xffff0000, v72
	v_lshlrev_b32_e32 v60, 16, v73
	v_and_b32_e32 v61, 0xffff0000, v73
	v_pk_add_f32 v[26:27], v[26:27], v[58:59]
	v_pk_add_f32 v[24:25], v[24:25], v[60:61]
	s_waitcnt vmcnt(26)
	v_lshlrev_b32_e32 v58, 16, v74
	v_and_b32_e32 v59, 0xffff0000, v74
	v_lshlrev_b32_e32 v60, 16, v75
	v_and_b32_e32 v61, 0xffff0000, v75
	v_pk_add_f32 v[30:31], v[30:31], v[58:59]
	v_pk_add_f32 v[28:29], v[28:29], v[60:61]
	s_waitcnt vmcnt(25)
	v_lshlrev_b32_e32 v58, 16, v76
	v_and_b32_e32 v59, 0xffff0000, v76
	v_lshlrev_b32_e32 v60, 16, v77
	v_and_b32_e32 v61, 0xffff0000, v77
	v_pk_add_f32 v[34:35], v[34:35], v[58:59]
	v_pk_add_f32 v[32:33], v[32:33], v[60:61]
	s_waitcnt vmcnt(24)
	v_lshlrev_b32_e32 v58, 16, v70
	v_and_b32_e32 v59, 0xffff0000, v70
	v_lshlrev_b32_e32 v60, 16, v71
	v_and_b32_e32 v61, 0xffff0000, v71
	v_pk_add_f32 v[36:37], v[36:37], v[58:59]
	v_pk_add_f32 v[38:39], v[38:39], v[60:61]
	s_waitcnt vmcnt(23)
	v_lshlrev_b32_e32 v58, 16, v80
	v_and_b32_e32 v59, 0xffff0000, v80
	v_lshlrev_b32_e32 v60, 16, v81
	v_and_b32_e32 v61, 0xffff0000, v81
	v_pk_add_f32 v[26:27], v[26:27], v[58:59]
	v_pk_add_f32 v[24:25], v[24:25], v[60:61]
	s_waitcnt vmcnt(22)
; __device__ __forceinline__ void phase_final(Ctx& C) {
;     ...
;         if (m >= MP) { const bf16* pp = (const bf16*)(C.ws + WS_PART) + (size_t)(m - MP) * D + 4 * lane;
;             for (int ks = 0; ks < 16; ++ks) {
; #pragma unroll
;                 for (int j = 0; j < 4; ++j) { const v2u pw = *(const v2u*)(pp + (size_t)ks * MS * D + 256 * j); v[j] += (f32x4){bflo(pw.x), bfhi(pw.x), bflo(pw.y), bfhi(pw.y)}; } } }
	v_lshlrev_b32_e32 v58, 16, v82
	v_and_b32_e32 v59, 0xffff0000, v82
	v_lshlrev_b32_e32 v60, 16, v83
	v_and_b32_e32 v61, 0xffff0000, v83
	v_pk_add_f32 v[30:31], v[30:31], v[58:59]
	v_pk_add_f32 v[28:29], v[28:29], v[60:61]
	s_waitcnt vmcnt(21)
	v_lshlrev_b32_e32 v58, 16, v84
	v_and_b32_e32 v59, 0xffff0000, v84
	v_lshlrev_b32_e32 v60, 16, v85
	v_and_b32_e32 v61, 0xffff0000, v85
	v_pk_add_f32 v[34:35], v[34:35], v[58:59]
	v_pk_add_f32 v[32:33], v[32:33], v[60:61]
	s_waitcnt vmcnt(20)
	v_lshlrev_b32_e32 v58, 16, v78
	v_and_b32_e32 v59, 0xffff0000, v78
	v_lshlrev_b32_e32 v60, 16, v79
	v_and_b32_e32 v61, 0xffff0000, v79
	v_pk_add_f32 v[36:37], v[36:37], v[58:59]
	v_pk_add_f32 v[38:39], v[38:39], v[60:61]
	s_waitcnt vmcnt(19)
	v_lshlrev_b32_e32 v58, 16, v88
	v_and_b32_e32 v59, 0xffff0000, v88
	v_lshlrev_b32_e32 v60, 16, v89
	v_and_b32_e32 v61, 0xffff0000, v89
	v_pk_add_f32 v[26:27], v[26:27], v[58:59]
	v_pk_add_f32 v[24:25], v[24:25], v[60:61]
	s_waitcnt vmcnt(18)
	v_lshlrev_b32_e32 v58, 16, v90
	v_and_b32_e32 v59, 0xffff0000, v90
	v_lshlrev_b32_e32 v60, 16, v91
	v_and_b32_e32 v61, 0xffff0000, v91
	v_pk_add_f32 v[30:31], v[30:31], v[58:59]
	v_pk_add_f32 v[28:29], v[28:29], v[60:61]
	s_waitcnt vmcnt(17)
	v_lshlrev_b32_e32 v58, 16, v92
	v_and_b32_e32 v59, 0xffff0000, v92
	v_lshlrev_b32_e32 v60, 16, v93
	v_and_b32_e32 v61, 0xffff0000, v93
	v_pk_add_f32 v[34:35], v[34:35], v[58:59]
	v_pk_add_f32 v[32:33], v[32:33], v[60:61]
	s_waitcnt vmcnt(16)
	v_lshlrev_b32_e32 v58, 16, v86
	v_and_b32_e32 v59, 0xffff0000, v86
	v_lshlrev_b32_e32 v60, 16, v87
	v_and_b32_e32 v61, 0xffff0000, v87
	v_pk_add_f32 v[36:37], v[36:37], v[58:59]
	v_pk_add_f32 v[38:39], v[38:39], v[60:61]
	s_waitcnt vmcnt(15)
	v_lshlrev_b32_e32 v58, 16, v96
	v_and_b32_e32 v59, 0xffff0000, v96
	v_lshlrev_b32_e32 v60, 16, v97
	v_and_b32_e32 v61, 0xffff0000, v97
	v_pk_add_f32 v[26:27], v[26:27], v[58:59]
	v_pk_add_f32 v[24:25], v[24:25], v[60:61]
	s_waitcnt vmcnt(14)
	v_lshlrev_b32_e32 v58, 16, v98
	v_and_b32_e32 v59, 0xffff0000, v98
	v_lshlrev_b32_e32 v60, 16, v99
	v_and_b32_e32 v61, 0xffff0000, v99
	v_pk_add_f32 v[30:31], v[30:31], v[58:59]
	v_pk_add_f32 v[28:29], v[28:29], v[60:61]
	s_waitcnt vmcnt(13)
	v_lshlrev_b32_e32 v58, 16, v100
	v_and_b32_e32 v59, 0xffff0000, v100
	v_lshlrev_b32_e32 v60, 16, v101
	v_and_b32_e32 v61, 0xffff0000, v101
	v_pk_add_f32 v[34:35], v[34:35], v[58:59]
	v_pk_add_f32 v[32:33], v[32:33], v[60:61]
	s_waitcnt vmcnt(12)
	v_lshlrev_b32_e32 v58, 16, v94
	v_and_b32_e32 v59, 0xffff0000, v94
	v_lshlrev_b32_e32 v60, 16, v95
	v_and_b32_e32 v61, 0xffff0000, v95
	v_pk_add_f32 v[36:37], v[36:37], v[58:59]
	v_pk_add_f32 v[38:39], v[38:39], v[60:61]
	s_waitcnt vmcnt(11)
	v_lshlrev_b32_e32 v58, 16, v104
	v_and_b32_e32 v59, 0xffff0000, v104
	v_lshlrev_b32_e32 v60, 16, v105
	v_and_b32_e32 v61, 0xffff0000, v105
	v_pk_add_f32 v[26:27], v[26:27], v[58:59]
	v_pk_add_f32 v[24:25], v[24:25], v[60:61]
	s_waitcnt vmcnt(10)
	v_lshlrev_b32_e32 v58, 16, v106
	v_and_b32_e32 v59, 0xffff0000, v106
	v_lshlrev_b32_e32 v60, 16, v107
	v_and_b32_e32 v61, 0xffff0000, v107
	v_pk_add_f32 v[30:31], v[30:31], v[58:59]
	v_pk_add_f32 v[28:29], v[28:29], v[60:61]
	s_waitcnt vmcnt(9)
	v_lshlrev_b32_e32 v58, 16, v108
	v_and_b32_e32 v59, 0xffff0000, v108
	v_lshlrev_b32_e32 v60, 16, v109
	v_and_b32_e32 v61, 0xffff0000, v109
	v_pk_add_f32 v[34:35], v[34:35], v[58:59]
	v_pk_add_f32 v[32:33], v[32:33], v[60:61]
	s_waitcnt vmcnt(8)
	v_lshlrev_b32_e32 v58, 16, v102
	v_and_b32_e32 v59, 0xffff0000, v102
	v_lshlrev_b32_e32 v60, 16, v103
	v_and_b32_e32 v61, 0xffff0000, v103
	v_pk_add_f32 v[36:37], v[36:37], v[58:59]
	v_pk_add_f32 v[38:39], v[38:39], v[60:61]
	s_waitcnt vmcnt(7)
	v_lshlrev_b32_e32 v58, 16, v112
	v_and_b32_e32 v59, 0xffff0000, v112
	v_lshlrev_b32_e32 v60, 16, v113
	v_and_b32_e32 v61, 0xffff0000, v113
	v_pk_add_f32 v[26:27], v[26:27], v[58:59]
	v_pk_add_f32 v[24:25], v[24:25], v[60:61]
	s_waitcnt vmcnt(6)
	v_lshlrev_b32_e32 v58, 16, v114
	v_and_b32_e32 v59, 0xffff0000, v114
	v_lshlrev_b32_e32 v60, 16, v115
	v_and_b32_e32 v61, 0xffff0000, v115
	v_pk_add_f32 v[30:31], v[30:31], v[58:59]
	v_pk_add_f32 v[28:29], v[28:29], v[60:61]
	s_waitcnt vmcnt(5)
	v_lshlrev_b32_e32 v58, 16, v116
	v_and_b32_e32 v59, 0xffff0000, v116
	v_lshlrev_b32_e32 v60, 16, v117
	v_and_b32_e32 v61, 0xffff0000, v117
	v_pk_add_f32 v[34:35], v[34:35], v[58:59]
	v_pk_add_f32 v[32:33], v[32:33], v[60:61]
	s_waitcnt vmcnt(4)
	v_lshlrev_b32_e32 v58, 16, v110
	v_and_b32_e32 v59, 0xffff0000, v110
	v_lshlrev_b32_e32 v60, 16, v111
	v_and_b32_e32 v61, 0xffff0000, v111
	v_pk_add_f32 v[36:37], v[36:37], v[58:59]
	v_pk_add_f32 v[38:39], v[38:39], v[60:61]
	s_waitcnt vmcnt(3)
	v_lshlrev_b32_e32 v58, 16, v120
	v_and_b32_e32 v59, 0xffff0000, v120
	v_lshlrev_b32_e32 v60, 16, v121
	v_and_b32_e32 v61, 0xffff0000, v121
	v_pk_add_f32 v[26:27], v[26:27], v[58:59]
	v_pk_add_f32 v[24:25], v[24:25], v[60:61]
	s_waitcnt vmcnt(2)
	v_lshlrev_b32_e32 v58, 16, v122
	v_and_b32_e32 v59, 0xffff0000, v122
	v_lshlrev_b32_e32 v60, 16, v123
	v_and_b32_e32 v61, 0xffff0000, v123
	v_pk_add_f32 v[30:31], v[30:31], v[58:59]
	v_pk_add_f32 v[28:29], v[28:29], v[60:61]
	s_waitcnt vmcnt(1)
	v_lshlrev_b32_e32 v58, 16, v124
	v_and_b32_e32 v59, 0xffff0000, v124
	v_lshlrev_b32_e32 v60, 16, v125
	v_and_b32_e32 v61, 0xffff0000, v125
	v_pk_add_f32 v[34:35], v[34:35], v[58:59]
	v_pk_add_f32 v[32:33], v[32:33], v[60:61]
	s_waitcnt vmcnt(0)
; __device__ __forceinline__ void phase_final(Ctx& C) {
;     ...
;         if (m >= MP) { const bf16* pp = (const bf16*)(C.ws + WS_PART) + (size_t)(m - MP) * D + 4 * lane;
;             for (int ks = 0; ks < 16; ++ks) {
; #pragma unroll
;                 for (int j = 0; j < 4; ++j) { const v2u pw = *(const v2u*)(pp + (size_t)ks * MS * D + 256 * j); v[j] += (f32x4){bflo(pw.x), bfhi(pw.x), bflo(pw.y), bfhi(pw.y)}; } } }
	v_lshlrev_b32_e32 v58, 16, v118
	v_and_b32_e32 v59, 0xffff0000, v118
	v_lshlrev_b32_e32 v60, 16, v119
	v_and_b32_e32 v61, 0xffff0000, v119
	v_pk_add_f32 v[36:37], v[36:37], v[58:59]
	v_pk_add_f32 v[38:39], v[38:39], v[60:61]
	s_mov_b32 s16, 0x1000000
	s_mov_b32 s17, 0x0
	v_lshl_add_u64 v[62:63], v[22:23], 0, s[16:17]
	global_load_dwordx2 v[64:65], v[62:63], off
	global_load_dwordx2 v[66:67], v[62:63], off offset:512
	global_load_dwordx2 v[68:69], v[62:63], off offset:1024
	global_load_dwordx2 v[62:63], v[62:63], off offset:1536
	s_mov_b32 s16, 0x1200000
	s_mov_b32 s17, 0x0
	v_lshl_add_u64 v[70:71], v[22:23], 0, s[16:17]
	global_load_dwordx2 v[72:73], v[70:71], off
	global_load_dwordx2 v[74:75], v[70:71], off offset:512
	global_load_dwordx2 v[76:77], v[70:71], off offset:1024
	global_load_dwordx2 v[70:71], v[70:71], off offset:1536
	s_mov_b32 s16, 0x1400000
	s_mov_b32 s17, 0x0
	v_lshl_add_u64 v[78:79], v[22:23], 0, s[16:17]
	global_load_dwordx2 v[80:81], v[78:79], off
	global_load_dwordx2 v[82:83], v[78:79], off offset:512
	global_load_dwordx2 v[84:85], v[78:79], off offset:1024
	global_load_dwordx2 v[78:79], v[78:79], off offset:1536
	s_mov_b32 s16, 0x1600000
	s_mov_b32 s17, 0x0
	v_lshl_add_u64 v[86:87], v[22:23], 0, s[16:17]
	global_load_dwordx2 v[88:89], v[86:87], off
	global_load_dwordx2 v[90:91], v[86:87], off offset:512
	global_load_dwordx2 v[92:93], v[86:87], off offset:1024
	global_load_dwordx2 v[86:87], v[86:87], off offset:1536
	s_mov_b32 s16, 0x1800000
	s_mov_b32 s17, 0x0
	v_lshl_add_u64 v[94:95], v[22:23], 0, s[16:17]
	global_load_dwordx2 v[96:97], v[94:95], off
	global_load_dwordx2 v[98:99], v[94:95], off offset:512
	global_load_dwordx2 v[100:101], v[94:95], off offset:1024
	global_load_dwordx2 v[94:95], v[94:95], off offset:1536
	s_mov_b32 s16, 0x1a00000
	s_mov_b32 s17, 0x0
	v_lshl_add_u64 v[102:103], v[22:23], 0, s[16:17]
	global_load_dwordx2 v[104:105], v[102:103], off
	global_load_dwordx2 v[106:107], v[102:103], off offset:512
	global_load_dwordx2 v[108:109], v[102:103], off offset:1024
	global_load_dwordx2 v[102:103], v[102:103], off offset:1536
	s_mov_b32 s16, 0x1c00000
	s_mov_b32 s17, 0x0
	v_lshl_add_u64 v[110:111], v[22:23], 0, s[16:17]
	global_load_dwordx2 v[112:113], v[110:111], off
	global_load_dwordx2 v[114:115], v[110:111], off offset:512
	global_load_dwordx2 v[116:117], v[110:111], off offset:1024
	global_load_dwordx2 v[110:111], v[110:111], off offset:1536
	s_mov_b32 s16, 0x1e00000
	s_mov_b32 s17, 0x0
	v_lshl_add_u64 v[118:119], v[22:23], 0, s[16:17]
	global_load_dwordx2 v[120:121], v[118:119], off
	global_load_dwordx2 v[122:123], v[118:119], off offset:512
	global_load_dwordx2 v[124:125], v[118:119], off offset:1024
	global_load_dwordx2 v[118:119], v[118:119], off offset:1536
	s_waitcnt vmcnt(31)
	v_lshlrev_b32_e32 v58, 16, v64
	v_and_b32_e32 v59, 0xffff0000, v64
	v_lshlrev_b32_e32 v60, 16, v65
	v_and_b32_e32 v61, 0xffff0000, v65
	v_pk_add_f32 v[26:27], v[26:27], v[58:59]
	v_pk_add_f32 v[24:25], v[24:25], v[60:61]
	s_waitcnt vmcnt(30)
	v_lshlrev_b32_e32 v58, 16, v66
	v_and_b32_e32 v59, 0xffff0000, v66
	v_lshlrev_b32_e32 v60, 16, v67
	v_and_b32_e32 v61, 0xffff0000, v67
	v_pk_add_f32 v[30:31], v[30:31], v[58:59]
	v_pk_add_f32 v[28:29], v[28:29], v[60:61]
	s_waitcnt vmcnt(29)
	v_lshlrev_b32_e32 v58, 16, v68
	v_and_b32_e32 v59, 0xffff0000, v68
	v_lshlrev_b32_e32 v60, 16, v69
	v_and_b32_e32 v61, 0xffff0000, v69
	v_pk_add_f32 v[34:35], v[34:35], v[58:59]
	v_pk_add_f32 v[32:33], v[32:33], v[60:61]
	s_waitcnt vmcnt(28)
	v_lshlrev_b32_e32 v58, 16, v62
	v_and_b32_e32 v59, 0xffff0000, v62
	v_lshlrev_b32_e32 v60, 16, v63
	v_and_b32_e32 v61, 0xffff0000, v63
	v_pk_add_f32 v[36:37], v[36:37], v[58:59]
	v_pk_add_f32 v[38:39], v[38:39], v[60:61]
	s_waitcnt vmcnt(27)
	v_lshlrev_b32_e32 v58, 16, v72
	v_and_b32_e32 v59, 0xffff0000, v72
	v_lshlrev_b32_e32 v60, 16, v73
	v_and_b32_e32 v61, 0xffff0000, v73
	v_pk_add_f32 v[26:27], v[26:27], v[58:59]
	v_pk_add_f32 v[24:25], v[24:25], v[60:61]
	s_waitcnt vmcnt(26)
	v_lshlrev_b32_e32 v58, 16, v74
	v_and_b32_e32 v59, 0xffff0000, v74
	v_lshlrev_b32_e32 v60, 16, v75
	v_and_b32_e32 v61, 0xffff0000, v75
	v_pk_add_f32 v[30:31], v[30:31], v[58:59]
	v_pk_add_f32 v[28:29], v[28:29], v[60:61]
	s_waitcnt vmcnt(25)
	v_lshlrev_b32_e32 v58, 16, v76
	v_and_b32_e32 v59, 0xffff0000, v76
	v_lshlrev_b32_e32 v60, 16, v77
	v_and_b32_e32 v61, 0xffff0000, v77
	v_pk_add_f32 v[34:35], v[34:35], v[58:59]
	v_pk_add_f32 v[32:33], v[32:33], v[60:61]
	s_waitcnt vmcnt(24)
	v_lshlrev_b32_e32 v58, 16, v70
	v_and_b32_e32 v59, 0xffff0000, v70
	v_lshlrev_b32_e32 v60, 16, v71
	v_and_b32_e32 v61, 0xffff0000, v71
	v_pk_add_f32 v[36:37], v[36:37], v[58:59]
	v_pk_add_f32 v[38:39], v[38:39], v[60:61]
	s_waitcnt vmcnt(23)
	v_lshlrev_b32_e32 v58, 16, v80
	v_and_b32_e32 v59, 0xffff0000, v80
	v_lshlrev_b32_e32 v60, 16, v81
	v_and_b32_e32 v61, 0xffff0000, v81
	v_pk_add_f32 v[26:27], v[26:27], v[58:59]
	v_pk_add_f32 v[24:25], v[24:25], v[60:61]
	s_waitcnt vmcnt(22)
	v_lshlrev_b32_e32 v58, 16, v82
	v_and_b32_e32 v59, 0xffff0000, v82
	v_lshlrev_b32_e32 v60, 16, v83
	v_and_b32_e32 v61, 0xffff0000, v83
	v_pk_add_f32 v[30:31], v[30:31], v[58:59]
	v_pk_add_f32 v[28:29], v[28:29], v[60:61]
	s_waitcnt vmcnt(21)
; __device__ __forceinline__ void phase_final(Ctx& C) {
;     ...
;         if (m >= MP) { const bf16* pp = (const bf16*)(C.ws + WS_PART) + (size_t)(m - MP) * D + 4 * lane;
;             for (int ks = 0; ks < 16; ++ks) {
; #pragma unroll
;                 for (int j = 0; j < 4; ++j) { const v2u pw = *(const v2u*)(pp + (size_t)ks * MS * D + 256 * j); v[j] += (f32x4){bflo(pw.x), bfhi(pw.x), bflo(pw.y), bfhi(pw.y)}; } } }
	v_lshlrev_b32_e32 v58, 16, v84
	v_and_b32_e32 v59, 0xffff0000, v84
	v_lshlrev_b32_e32 v60, 16, v85
	v_and_b32_e32 v61, 0xffff0000, v85
	v_pk_add_f32 v[34:35], v[34:35], v[58:59]
	v_pk_add_f32 v[32:33], v[32:33], v[60:61]
	s_waitcnt vmcnt(20)
	v_lshlrev_b32_e32 v58, 16, v78
	v_and_b32_e32 v59, 0xffff0000, v78
	v_lshlrev_b32_e32 v60, 16, v79
	v_and_b32_e32 v61, 0xffff0000, v79
	v_pk_add_f32 v[36:37], v[36:37], v[58:59]
	v_pk_add_f32 v[38:39], v[38:39], v[60:61]
	s_waitcnt vmcnt(19)
	v_lshlrev_b32_e32 v58, 16, v88
	v_and_b32_e32 v59, 0xffff0000, v88
	v_lshlrev_b32_e32 v60, 16, v89
	v_and_b32_e32 v61, 0xffff0000, v89
	v_pk_add_f32 v[26:27], v[26:27], v[58:59]
	v_pk_add_f32 v[24:25], v[24:25], v[60:61]
	s_waitcnt vmcnt(18)
	v_lshlrev_b32_e32 v58, 16, v90
	v_and_b32_e32 v59, 0xffff0000, v90
	v_lshlrev_b32_e32 v60, 16, v91
	v_and_b32_e32 v61, 0xffff0000, v91
	v_pk_add_f32 v[30:31], v[30:31], v[58:59]
	v_pk_add_f32 v[28:29], v[28:29], v[60:61]
	s_waitcnt vmcnt(17)
	v_lshlrev_b32_e32 v58, 16, v92
	v_and_b32_e32 v59, 0xffff0000, v92
	v_lshlrev_b32_e32 v60, 16, v93
	v_and_b32_e32 v61, 0xffff0000, v93
	v_pk_add_f32 v[34:35], v[34:35], v[58:59]
	v_pk_add_f32 v[32:33], v[32:33], v[60:61]
	s_waitcnt vmcnt(16)
	v_lshlrev_b32_e32 v58, 16, v86
	v_and_b32_e32 v59, 0xffff0000, v86
	v_lshlrev_b32_e32 v60, 16, v87
	v_and_b32_e32 v61, 0xffff0000, v87
	v_pk_add_f32 v[36:37], v[36:37], v[58:59]
	v_pk_add_f32 v[38:39], v[38:39], v[60:61]
	s_waitcnt vmcnt(15)
	v_lshlrev_b32_e32 v58, 16, v96
	v_and_b32_e32 v59, 0xffff0000, v96
	v_lshlrev_b32_e32 v60, 16, v97
	v_and_b32_e32 v61, 0xffff0000, v97
	v_pk_add_f32 v[26:27], v[26:27], v[58:59]
	v_pk_add_f32 v[24:25], v[24:25], v[60:61]
	s_waitcnt vmcnt(14)
	v_lshlrev_b32_e32 v58, 16, v98
	v_and_b32_e32 v59, 0xffff0000, v98
	v_lshlrev_b32_e32 v60, 16, v99
	v_and_b32_e32 v61, 0xffff0000, v99
	v_pk_add_f32 v[30:31], v[30:31], v[58:59]
	v_pk_add_f32 v[28:29], v[28:29], v[60:61]
	s_waitcnt vmcnt(13)
	v_lshlrev_b32_e32 v58, 16, v100
	v_and_b32_e32 v59, 0xffff0000, v100
	v_lshlrev_b32_e32 v60, 16, v101
	v_and_b32_e32 v61, 0xffff0000, v101
	v_pk_add_f32 v[34:35], v[34:35], v[58:59]
	v_pk_add_f32 v[32:33], v[32:33], v[60:61]
	s_waitcnt vmcnt(12)
	v_lshlrev_b32_e32 v58, 16, v94
	v_and_b32_e32 v59, 0xffff0000, v94
	v_lshlrev_b32_e32 v60, 16, v95
	v_and_b32_e32 v61, 0xffff0000, v95
	v_pk_add_f32 v[36:37], v[36:37], v[58:59]
	v_pk_add_f32 v[38:39], v[38:39], v[60:61]
	s_waitcnt vmcnt(11)
	v_lshlrev_b32_e32 v58, 16, v104
	v_and_b32_e32 v59, 0xffff0000, v104
	v_lshlrev_b32_e32 v60, 16, v105
	v_and_b32_e32 v61, 0xffff0000, v105
	v_pk_add_f32 v[26:27], v[26:27], v[58:59]
	v_pk_add_f32 v[24:25], v[24:25], v[60:61]
	s_waitcnt vmcnt(10)
	v_lshlrev_b32_e32 v58, 16, v106
	v_and_b32_e32 v59, 0xffff0000, v106
	v_lshlrev_b32_e32 v60, 16, v107
	v_and_b32_e32 v61, 0xffff0000, v107
	v_pk_add_f32 v[30:31], v[30:31], v[58:59]
	v_pk_add_f32 v[28:29], v[28:29], v[60:61]
	s_waitcnt vmcnt(9)
	v_lshlrev_b32_e32 v58, 16, v108
	v_and_b32_e32 v59, 0xffff0000, v108
	v_lshlrev_b32_e32 v60, 16, v109
	v_and_b32_e32 v61, 0xffff0000, v109
	v_pk_add_f32 v[34:35], v[34:35], v[58:59]
	v_pk_add_f32 v[32:33], v[32:33], v[60:61]
	s_waitcnt vmcnt(8)
	v_lshlrev_b32_e32 v58, 16, v102
	v_and_b32_e32 v59, 0xffff0000, v102
	v_lshlrev_b32_e32 v60, 16, v103
	v_and_b32_e32 v61, 0xffff0000, v103
	v_pk_add_f32 v[36:37], v[36:37], v[58:59]
	v_pk_add_f32 v[38:39], v[38:39], v[60:61]
	s_waitcnt vmcnt(7)
	v_lshlrev_b32_e32 v58, 16, v112
	v_and_b32_e32 v59, 0xffff0000, v112
	v_lshlrev_b32_e32 v60, 16, v113
	v_and_b32_e32 v61, 0xffff0000, v113
	v_pk_add_f32 v[26:27], v[26:27], v[58:59]
	v_pk_add_f32 v[24:25], v[24:25], v[60:61]
	s_waitcnt vmcnt(6)
	v_lshlrev_b32_e32 v58, 16, v114
	v_and_b32_e32 v59, 0xffff0000, v114
	v_lshlrev_b32_e32 v60, 16, v115
	v_and_b32_e32 v61, 0xffff0000, v115
	v_pk_add_f32 v[30:31], v[30:31], v[58:59]
	v_pk_add_f32 v[28:29], v[28:29], v[60:61]
	s_waitcnt vmcnt(5)
	v_lshlrev_b32_e32 v58, 16, v116
	v_and_b32_e32 v59, 0xffff0000, v116
	v_lshlrev_b32_e32 v60, 16, v117
	v_and_b32_e32 v61, 0xffff0000, v117
	v_pk_add_f32 v[34:35], v[34:35], v[58:59]
	v_pk_add_f32 v[32:33], v[32:33], v[60:61]
	s_waitcnt vmcnt(4)
	v_lshlrev_b32_e32 v58, 16, v110
	v_and_b32_e32 v59, 0xffff0000, v110
	v_lshlrev_b32_e32 v60, 16, v111
	v_and_b32_e32 v61, 0xffff0000, v111
	v_pk_add_f32 v[36:37], v[36:37], v[58:59]
	v_pk_add_f32 v[38:39], v[38:39], v[60:61]
	s_waitcnt vmcnt(3)
	v_lshlrev_b32_e32 v58, 16, v120
	v_and_b32_e32 v59, 0xffff0000, v120
	v_lshlrev_b32_e32 v60, 16, v121
	v_and_b32_e32 v61, 0xffff0000, v121
	v_pk_add_f32 v[26:27], v[26:27], v[58:59]
	v_pk_add_f32 v[24:25], v[24:25], v[60:61]
	s_waitcnt vmcnt(2)
	v_lshlrev_b32_e32 v58, 16, v122
	v_and_b32_e32 v59, 0xffff0000, v122
	v_lshlrev_b32_e32 v60, 16, v123
	v_and_b32_e32 v61, 0xffff0000, v123
	v_pk_add_f32 v[30:31], v[30:31], v[58:59]
	v_pk_add_f32 v[28:29], v[28:29], v[60:61]
	s_waitcnt vmcnt(1)
	v_lshlrev_b32_e32 v58, 16, v124
	v_and_b32_e32 v59, 0xffff0000, v124
	v_lshlrev_b32_e32 v60, 16, v125
	v_and_b32_e32 v61, 0xffff0000, v125
	v_pk_add_f32 v[34:35], v[34:35], v[58:59]
	v_pk_add_f32 v[32:33], v[32:33], v[60:61]
	s_waitcnt vmcnt(0)
	v_lshlrev_b32_e32 v58, 16, v118
	v_and_b32_e32 v59, 0xffff0000, v118
	v_lshlrev_b32_e32 v60, 16, v119
	v_and_b32_e32 v61, 0xffff0000, v119
	v_pk_add_f32 v[36:37], v[36:37], v[58:59]
	v_pk_add_f32 v[38:39], v[38:39], v[60:61]
	s_branch .LBB0_2117
